# GEMM main loops (QKV, mixer, up, down): per-cluster s_setprio flips deleted; one static s_setprio 1 for the leading wave group before the loop, back to 0 at loop exit
# speedup vs baseline: 1.0193x; 1.0022x over previous
.LBB0_311:
	s_ashr_i32 s21, s20, 31
	s_lshl_b64 s[22:23], s[20:21], 19
	s_add_u32 s22, s86, s22
	s_addc_u32 s23, s87, s23
	s_and_b64 s[24:25], s[2:3], exec
	s_cselect_b32 s21, s23, s5
	s_cselect_b32 s35, s22, s4
	s_ashr_i32 s19, s18, 31
	s_lshl_b64 s[24:25], s[18:19], 19
	s_add_u32 s24, s88, s24
	s_addc_u32 s25, s89, s25
	s_and_b64 s[66:67], s[2:3], exec
	s_cselect_b32 s19, s25, s7
	s_cselect_b32 s68, s24, s6
	s_add_u32 s4, s4, 0x40080
	s_addc_u32 s5, s5, 0
	s_add_u32 s69, s6, 0x100
	v_mov_b32_e32 v0, 0
	s_addc_u32 s72, s7, 0
	s_mov_b32 s73, -2
	v_mov_b32_e32 v1, v0
	v_mov_b32_e32 v2, v0
	v_mov_b32_e32 v3, v0
	v_mov_b32_e32 v4, v0
	v_mov_b32_e32 v5, v0
	v_mov_b32_e32 v6, v0
	v_mov_b32_e32 v7, v0
	v_mov_b32_e32 v16, v0
	v_mov_b32_e32 v17, v0
	v_mov_b32_e32 v18, v0
	v_mov_b32_e32 v19, v0
	v_mov_b32_e32 v20, v0
	v_mov_b32_e32 v21, v0
	v_mov_b32_e32 v22, v0
	v_mov_b32_e32 v23, v0
	v_mov_b32_e32 v32, v0
	v_mov_b32_e32 v33, v0
	v_mov_b32_e32 v34, v0
	v_mov_b32_e32 v35, v0
	v_mov_b32_e32 v36, v0
	v_mov_b32_e32 v37, v0
	v_mov_b32_e32 v38, v0
	v_mov_b32_e32 v39, v0
	v_mov_b32_e32 v48, v0
	v_mov_b32_e32 v49, v0
	v_mov_b32_e32 v50, v0
	v_mov_b32_e32 v51, v0
	v_mov_b32_e32 v52, v0
	v_mov_b32_e32 v53, v0
	v_mov_b32_e32 v54, v0
	v_mov_b32_e32 v55, v0
	v_mov_b32_e32 v8, v0
	v_mov_b32_e32 v9, v0
	v_mov_b32_e32 v10, v0
	v_mov_b32_e32 v11, v0
	v_mov_b32_e32 v12, v0
	v_mov_b32_e32 v13, v0
	v_mov_b32_e32 v14, v0
	v_mov_b32_e32 v15, v0
	v_mov_b32_e32 v24, v0
	v_mov_b32_e32 v25, v0
	v_mov_b32_e32 v26, v0
	v_mov_b32_e32 v27, v0
	v_mov_b32_e32 v28, v0
	v_mov_b32_e32 v29, v0
	v_mov_b32_e32 v30, v0
	v_mov_b32_e32 v31, v0
	v_mov_b32_e32 v40, v0
	v_mov_b32_e32 v41, v0
	v_mov_b32_e32 v42, v0
	v_mov_b32_e32 v43, v0
	v_mov_b32_e32 v44, v0
	v_mov_b32_e32 v45, v0
	v_mov_b32_e32 v46, v0
	v_mov_b32_e32 v47, v0
	v_mov_b32_e32 v56, v0
	v_mov_b32_e32 v57, v0
	v_mov_b32_e32 v58, v0
	v_mov_b32_e32 v59, v0
	v_mov_b32_e32 v60, v0
	v_mov_b32_e32 v61, v0
	v_mov_b32_e32 v62, v0
	v_mov_b32_e32 v63, v0
	v_mov_b32_e32 v64, v0
	v_mov_b32_e32 v65, v0
	v_mov_b32_e32 v66, v0
	v_mov_b32_e32 v67, v0
	v_mov_b32_e32 v68, v0
	v_mov_b32_e32 v69, v0
	v_mov_b32_e32 v70, v0
	v_mov_b32_e32 v71, v0
	v_mov_b32_e32 v80, v0
	v_mov_b32_e32 v81, v0
	v_mov_b32_e32 v82, v0
	v_mov_b32_e32 v83, v0
	v_mov_b32_e32 v84, v0
	v_mov_b32_e32 v85, v0
	v_mov_b32_e32 v86, v0
	v_mov_b32_e32 v87, v0
	v_mov_b32_e32 v98, v0
	v_mov_b32_e32 v99, v0
	v_mov_b32_e32 v100, v0
	v_mov_b32_e32 v101, v0
	v_mov_b32_e32 v102, v0
	v_mov_b32_e32 v103, v0
	v_mov_b32_e32 v104, v0
	v_mov_b32_e32 v105, v0
	v_mov_b32_e32 v114, v0
	v_mov_b32_e32 v115, v0
	v_mov_b32_e32 v116, v0
	v_mov_b32_e32 v117, v0
	v_mov_b32_e32 v118, v0
	v_mov_b32_e32 v119, v0
	v_mov_b32_e32 v120, v0
	v_mov_b32_e32 v121, v0
	v_mov_b32_e32 v72, v0
	v_mov_b32_e32 v73, v0
	v_mov_b32_e32 v74, v0
	v_mov_b32_e32 v75, v0
	v_mov_b32_e32 v76, v0
	v_mov_b32_e32 v77, v0
	v_mov_b32_e32 v78, v0
	v_mov_b32_e32 v79, v0
	v_mov_b32_e32 v88, v0
	v_mov_b32_e32 v89, v0
	v_mov_b32_e32 v90, v0
	v_mov_b32_e32 v91, v0
	v_mov_b32_e32 v92, v0
	v_mov_b32_e32 v93, v0
	v_mov_b32_e32 v94, v0
	v_mov_b32_e32 v95, v0
	v_mov_b32_e32 v106, v0
	v_mov_b32_e32 v107, v0
	v_mov_b32_e32 v108, v0
	v_mov_b32_e32 v109, v0
	v_mov_b32_e32 v110, v0
	v_mov_b32_e32 v111, v0
	v_mov_b32_e32 v112, v0
	v_mov_b32_e32 v113, v0
	v_mov_b32_e32 v122, v0
	v_mov_b32_e32 v123, v0
	v_mov_b32_e32 v124, v0
	v_mov_b32_e32 v125, v0
	v_mov_b32_e32 v126, v0
	v_mov_b32_e32 v127, v0
	v_mov_b32_e32 v128, v0
	v_mov_b32_e32 v129, v0
	s_cmp_eq_u32 s84, 0
	s_cbranch_scc0 .Lsprio_skip0
	s_setprio 1
.Lsprio_skip0:
.LBB0_312:
	s_add_u32 s6, s4, 0xfffc0080
	s_addc_u32 s7, s5, -1
	s_add_i32 s30, 0, 0x10000
	s_cmp_eq_u32 s73, 12
	s_cselect_b32 s67, s21, s7
	s_cselect_b32 s66, s35, s6
	v_add_u32_e32 v96, s30, v180
	s_cselect_b32 s7, s19, s72
	s_cselect_b32 s6, s68, s69
	s_add_i32 s31, 0, 0x14000
	ds_read_b128 v[130:133], v96
	ds_read_b128 v[134:137], v96 offset:1024
	ds_read_b128 v[150:153], v96 offset:2048
	ds_read_b128 v[154:157], v96 offset:3072
	v_add_u32_e32 v96, s31, v180
	ds_read_b128 v[158:161], v96
	ds_read_b128 v[162:165], v96 offset:1024
	ds_read_b128 v[166:169], v96 offset:2048
	ds_read_b128 v[170:173], v96 offset:3072
	v_lshl_add_u64 v[210:211], s[4:5], 0, v[146:147]
	s_add_i32 m0, s27, 0xc000
	ds_read_b128 v[174:177], v181
	ds_read_b128 v[182:185], v181 offset:1024
	ds_read_b128 v[186:189], v181 offset:2048
	ds_read_b128 v[190:193], v181 offset:3072
	ds_read_b128 v[194:197], v181 offset:4096
	ds_read_b128 v[198:201], v181 offset:5120
	ds_read_b128 v[202:205], v181 offset:6144
	ds_read_b128 v[206:209], v181 offset:7168
	global_load_lds_dwordx4 v[210:211], off
	v_lshl_add_u64 v[210:211], s[4:5], 0, v[148:149]
	s_add_i32 m0, s27, 0xe000
	s_nop 0
	global_load_lds_dwordx4 v[210:211], off
	s_waitcnt vmcnt(8)
	s_waitcnt lgkmcnt(0)
	s_barrier
	s_waitcnt lgkmcnt(0)
	v_mfma_f32_16x16x32_bf16 v[126:129], v[130:133], v[174:177], v[126:129]
	v_mfma_f32_16x16x32_bf16 v[122:125], v[150:153], v[174:177], v[122:125]
	v_mfma_f32_16x16x32_bf16 v[110:113], v[130:133], v[186:189], v[110:113]
	v_mfma_f32_16x16x32_bf16 v[106:109], v[150:153], v[186:189], v[106:109]
	v_mfma_f32_16x16x32_bf16 v[92:95], v[130:133], v[194:197], v[92:95]
	v_mfma_f32_16x16x32_bf16 v[88:91], v[150:153], v[194:197], v[88:91]
	v_mfma_f32_16x16x32_bf16 v[76:79], v[130:133], v[202:205], v[76:79]
	v_mfma_f32_16x16x32_bf16 v[72:75], v[150:153], v[202:205], v[72:75]
	v_mfma_f32_16x16x32_bf16 v[126:129], v[134:137], v[182:185], v[126:129]
	v_mfma_f32_16x16x32_bf16 v[122:125], v[154:157], v[182:185], v[122:125]
	v_mfma_f32_16x16x32_bf16 v[110:113], v[134:137], v[190:193], v[110:113]
	v_mfma_f32_16x16x32_bf16 v[106:109], v[154:157], v[190:193], v[106:109]
	v_mfma_f32_16x16x32_bf16 v[92:95], v[134:137], v[198:201], v[92:95]
	v_mfma_f32_16x16x32_bf16 v[88:91], v[154:157], v[198:201], v[88:91]
	v_mfma_f32_16x16x32_bf16 v[76:79], v[134:137], v[206:209], v[76:79]
	v_mfma_f32_16x16x32_bf16 v[72:75], v[154:157], v[206:209], v[72:75]
	v_mfma_f32_16x16x32_bf16 v[118:121], v[158:161], v[174:177], v[118:121]
	v_mfma_f32_16x16x32_bf16 v[114:117], v[166:169], v[174:177], v[114:117]
	v_mfma_f32_16x16x32_bf16 v[102:105], v[158:161], v[186:189], v[102:105]
	v_mfma_f32_16x16x32_bf16 v[98:101], v[166:169], v[186:189], v[98:101]
	v_mfma_f32_16x16x32_bf16 v[84:87], v[158:161], v[194:197], v[84:87]
	v_mfma_f32_16x16x32_bf16 v[80:83], v[166:169], v[194:197], v[80:83]
	v_mfma_f32_16x16x32_bf16 v[68:71], v[158:161], v[202:205], v[68:71]
	v_mfma_f32_16x16x32_bf16 v[64:67], v[166:169], v[202:205], v[64:67]
	v_mfma_f32_16x16x32_bf16 v[118:121], v[162:165], v[182:185], v[118:121]
	v_mfma_f32_16x16x32_bf16 v[114:117], v[170:173], v[182:185], v[114:117]
	v_mfma_f32_16x16x32_bf16 v[102:105], v[162:165], v[190:193], v[102:105]
	v_mfma_f32_16x16x32_bf16 v[98:101], v[170:173], v[190:193], v[98:101]
	v_mfma_f32_16x16x32_bf16 v[84:87], v[162:165], v[198:201], v[84:87]
	v_mfma_f32_16x16x32_bf16 v[80:83], v[170:173], v[198:201], v[80:83]
	v_mfma_f32_16x16x32_bf16 v[68:71], v[162:165], v[206:209], v[68:71]
	v_mfma_f32_16x16x32_bf16 v[64:67], v[170:173], v[206:209], v[64:67]
	s_barrier
	s_add_i32 s30, s30, s85
	v_lshl_add_u64 v[210:211], s[6:7], 0, v[140:141]
	s_mov_b32 m0, s30
	ds_read_b128 v[174:177], v181 offset:16384
	ds_read_b128 v[182:185], v181 offset:17408
	ds_read_b128 v[186:189], v181 offset:18432
	ds_read_b128 v[190:193], v181 offset:19456
	ds_read_b128 v[194:197], v181 offset:20480
	ds_read_b128 v[198:201], v181 offset:21504
	ds_read_b128 v[202:205], v181 offset:22528
	ds_read_b128 v[206:209], v181 offset:23552
	global_load_lds_dwordx4 v[210:211], off
	s_add_i32 m0, s30, 0x2000
	s_add_u32 s74, s6, 0x40000
	v_lshl_add_u64 v[216:217], s[6:7], 0, v[144:145]
	s_addc_u32 s75, s7, 0
	s_add_i32 s30, s31, s85
	global_load_lds_dwordx4 v[216:217], off
	v_lshl_add_u64 v[218:219], s[74:75], 0, v[140:141]
	s_mov_b32 m0, s30
	v_lshl_add_u64 v[220:221], s[66:67], 0, v[142:143]
	global_load_lds_dwordx4 v[218:219], off
	v_lshl_add_u64 v[218:219], s[74:75], 0, v[144:145]
	s_add_i32 m0, s30, 0x2000
	s_nop 0
	global_load_lds_dwordx4 v[218:219], off
	v_lshl_add_u64 v[218:219], s[66:67], 0, v[138:139]
	s_mov_b32 m0, s27
	s_nop 0
	global_load_lds_dwordx4 v[218:219], off
	s_mov_b32 m0, s71
	s_nop 0
	global_load_lds_dwordx4 v[220:221], off
	s_waitcnt vmcnt(8)
	s_waitcnt lgkmcnt(0)
	s_barrier
	s_waitcnt lgkmcnt(0)
	v_mfma_f32_16x16x32_bf16 v[60:63], v[130:133], v[174:177], v[60:63]
	v_mfma_f32_16x16x32_bf16 v[56:59], v[150:153], v[174:177], v[56:59]
	v_mfma_f32_16x16x32_bf16 v[44:47], v[130:133], v[186:189], v[44:47]
	v_mfma_f32_16x16x32_bf16 v[40:43], v[150:153], v[186:189], v[40:43]
	v_mfma_f32_16x16x32_bf16 v[28:31], v[130:133], v[194:197], v[28:31]
	v_mfma_f32_16x16x32_bf16 v[24:27], v[150:153], v[194:197], v[24:27]
	v_mfma_f32_16x16x32_bf16 v[12:15], v[130:133], v[202:205], v[12:15]
	v_mfma_f32_16x16x32_bf16 v[8:11], v[150:153], v[202:205], v[8:11]
	v_mfma_f32_16x16x32_bf16 v[60:63], v[134:137], v[182:185], v[60:63]
	v_mfma_f32_16x16x32_bf16 v[56:59], v[154:157], v[182:185], v[56:59]
	v_mfma_f32_16x16x32_bf16 v[44:47], v[134:137], v[190:193], v[44:47]
	v_mfma_f32_16x16x32_bf16 v[40:43], v[154:157], v[190:193], v[40:43]
	v_mfma_f32_16x16x32_bf16 v[28:31], v[134:137], v[198:201], v[28:31]
	v_mfma_f32_16x16x32_bf16 v[24:27], v[154:157], v[198:201], v[24:27]
	v_mfma_f32_16x16x32_bf16 v[12:15], v[134:137], v[206:209], v[12:15]
	v_mfma_f32_16x16x32_bf16 v[8:11], v[154:157], v[206:209], v[8:11]
	v_mfma_f32_16x16x32_bf16 v[52:55], v[158:161], v[174:177], v[52:55]
	v_mfma_f32_16x16x32_bf16 v[48:51], v[166:169], v[174:177], v[48:51]
	v_mfma_f32_16x16x32_bf16 v[36:39], v[158:161], v[186:189], v[36:39]
	v_mfma_f32_16x16x32_bf16 v[32:35], v[166:169], v[186:189], v[32:35]
	v_mfma_f32_16x16x32_bf16 v[20:23], v[158:161], v[194:197], v[20:23]
	v_mfma_f32_16x16x32_bf16 v[16:19], v[166:169], v[194:197], v[16:19]
	v_mfma_f32_16x16x32_bf16 v[4:7], v[158:161], v[202:205], v[4:7]
	v_mfma_f32_16x16x32_bf16 v[0:3], v[166:169], v[202:205], v[0:3]
	v_mfma_f32_16x16x32_bf16 v[52:55], v[162:165], v[182:185], v[52:55]
	v_mfma_f32_16x16x32_bf16 v[48:51], v[170:173], v[182:185], v[48:51]
	v_mfma_f32_16x16x32_bf16 v[36:39], v[162:165], v[190:193], v[36:39]
	v_mfma_f32_16x16x32_bf16 v[32:35], v[170:173], v[190:193], v[32:35]
	v_mfma_f32_16x16x32_bf16 v[20:23], v[162:165], v[198:201], v[20:23]
	v_mfma_f32_16x16x32_bf16 v[16:19], v[170:173], v[198:201], v[16:19]
	v_mfma_f32_16x16x32_bf16 v[4:7], v[162:165], v[206:209], v[4:7]
	v_mfma_f32_16x16x32_bf16 v[0:3], v[170:173], v[206:209], v[0:3]
	s_barrier
	s_add_i32 s30, 0, 0x18000
	v_add_u32_e32 v96, s30, v180
	s_add_i32 s31, 0, 0x1c000
	ds_read_b128 v[130:133], v96
	ds_read_b128 v[134:137], v96 offset:1024
	ds_read_b128 v[150:153], v96 offset:2048
	ds_read_b128 v[154:157], v96 offset:3072
	v_add_u32_e32 v96, s31, v180
	ds_read_b128 v[158:161], v96
	ds_read_b128 v[162:165], v96 offset:1024
	ds_read_b128 v[166:169], v96 offset:2048
	ds_read_b128 v[170:173], v96 offset:3072
	s_add_u32 s66, s66, 0x40000
	s_addc_u32 s67, s67, 0
	s_mov_b32 m0, s90
	v_lshl_add_u64 v[222:223], s[66:67], 0, v[138:139]
	ds_read_b128 v[174:177], v181 offset:32768
	ds_read_b128 v[182:185], v181 offset:33792
	ds_read_b128 v[186:189], v181 offset:34816
	ds_read_b128 v[190:193], v181 offset:35840
	ds_read_b128 v[194:197], v181 offset:36864
	ds_read_b128 v[198:201], v181 offset:37888
	ds_read_b128 v[202:205], v181 offset:38912
	ds_read_b128 v[206:209], v181 offset:39936
	global_load_lds_dwordx4 v[222:223], off
	v_lshl_add_u64 v[222:223], s[66:67], 0, v[142:143]
	s_mov_b32 m0, s91
	s_nop 0
	global_load_lds_dwordx4 v[222:223], off
	s_waitcnt vmcnt(8)
	s_waitcnt lgkmcnt(0)
	s_barrier
	s_waitcnt lgkmcnt(0)
	v_mfma_f32_16x16x32_bf16 v[126:129], v[130:133], v[174:177], v[126:129]
	v_mfma_f32_16x16x32_bf16 v[122:125], v[150:153], v[174:177], v[122:125]
	v_mfma_f32_16x16x32_bf16 v[110:113], v[130:133], v[186:189], v[110:113]
	v_mfma_f32_16x16x32_bf16 v[106:109], v[150:153], v[186:189], v[106:109]
	v_mfma_f32_16x16x32_bf16 v[92:95], v[130:133], v[194:197], v[92:95]
	v_mfma_f32_16x16x32_bf16 v[88:91], v[150:153], v[194:197], v[88:91]
	v_mfma_f32_16x16x32_bf16 v[76:79], v[130:133], v[202:205], v[76:79]
	v_mfma_f32_16x16x32_bf16 v[72:75], v[150:153], v[202:205], v[72:75]
	v_mfma_f32_16x16x32_bf16 v[126:129], v[134:137], v[182:185], v[126:129]
	v_mfma_f32_16x16x32_bf16 v[122:125], v[154:157], v[182:185], v[122:125]
	v_mfma_f32_16x16x32_bf16 v[110:113], v[134:137], v[190:193], v[110:113]
	v_mfma_f32_16x16x32_bf16 v[106:109], v[154:157], v[190:193], v[106:109]
	v_mfma_f32_16x16x32_bf16 v[92:95], v[134:137], v[198:201], v[92:95]
	v_mfma_f32_16x16x32_bf16 v[88:91], v[154:157], v[198:201], v[88:91]
	v_mfma_f32_16x16x32_bf16 v[76:79], v[134:137], v[206:209], v[76:79]
	v_mfma_f32_16x16x32_bf16 v[72:75], v[154:157], v[206:209], v[72:75]
	v_mfma_f32_16x16x32_bf16 v[118:121], v[158:161], v[174:177], v[118:121]
	v_mfma_f32_16x16x32_bf16 v[114:117], v[166:169], v[174:177], v[114:117]
	v_mfma_f32_16x16x32_bf16 v[102:105], v[158:161], v[186:189], v[102:105]
	v_mfma_f32_16x16x32_bf16 v[98:101], v[166:169], v[186:189], v[98:101]
	v_mfma_f32_16x16x32_bf16 v[84:87], v[158:161], v[194:197], v[84:87]
	v_mfma_f32_16x16x32_bf16 v[80:83], v[166:169], v[194:197], v[80:83]
	v_mfma_f32_16x16x32_bf16 v[68:71], v[158:161], v[202:205], v[68:71]
	v_mfma_f32_16x16x32_bf16 v[64:67], v[166:169], v[202:205], v[64:67]
	v_mfma_f32_16x16x32_bf16 v[118:121], v[162:165], v[182:185], v[118:121]
	v_mfma_f32_16x16x32_bf16 v[114:117], v[170:173], v[182:185], v[114:117]
	v_mfma_f32_16x16x32_bf16 v[102:105], v[162:165], v[190:193], v[102:105]
	v_mfma_f32_16x16x32_bf16 v[98:101], v[170:173], v[190:193], v[98:101]
	v_mfma_f32_16x16x32_bf16 v[84:87], v[162:165], v[198:201], v[84:87]
	v_mfma_f32_16x16x32_bf16 v[80:83], v[170:173], v[198:201], v[80:83]
	v_mfma_f32_16x16x32_bf16 v[68:71], v[162:165], v[206:209], v[68:71]
	v_mfma_f32_16x16x32_bf16 v[64:67], v[170:173], v[206:209], v[64:67]
	s_barrier
	s_add_i32 s30, s30, s85
	v_lshl_add_u64 v[210:211], v[210:211], 0, s[48:49]
	s_mov_b32 m0, s30
	ds_read_b128 v[174:177], v181 offset:49152
	ds_read_b128 v[182:185], v181 offset:50176
	ds_read_b128 v[186:189], v181 offset:51200
	ds_read_b128 v[190:193], v181 offset:52224
	ds_read_b128 v[194:197], v181 offset:53248
	ds_read_b128 v[198:201], v181 offset:54272
	ds_read_b128 v[202:205], v181 offset:55296
	ds_read_b128 v[206:209], v181 offset:56320
	global_load_lds_dwordx4 v[210:211], off
	s_add_i32 m0, s30, 0x2000
	s_add_u32 s6, s6, 0x40080
	v_lshl_add_u64 v[210:211], v[216:217], 0, s[48:49]
	s_addc_u32 s7, s7, 0
	s_add_i32 s30, s31, s85
	global_load_lds_dwordx4 v[210:211], off
	v_lshl_add_u64 v[210:211], s[6:7], 0, v[140:141]
	s_mov_b32 m0, s30
	s_nop 0
	global_load_lds_dwordx4 v[210:211], off
	v_lshl_add_u64 v[210:211], s[6:7], 0, v[144:145]
	s_add_i32 m0, s30, 0x2000
	s_nop 0
	global_load_lds_dwordx4 v[210:211], off
	v_lshl_add_u64 v[210:211], v[218:219], 0, s[48:49]
	s_mov_b32 m0, s63
	s_nop 0
	global_load_lds_dwordx4 v[210:211], off
	v_lshl_add_u64 v[210:211], v[220:221], 0, s[48:49]
	s_mov_b32 m0, s96
	s_nop 0
	global_load_lds_dwordx4 v[210:211], off
	s_waitcnt vmcnt(8)
	s_waitcnt lgkmcnt(0)
	s_barrier
	s_waitcnt lgkmcnt(0)
	v_mfma_f32_16x16x32_bf16 v[60:63], v[130:133], v[174:177], v[60:63]
	v_mfma_f32_16x16x32_bf16 v[56:59], v[150:153], v[174:177], v[56:59]
	v_mfma_f32_16x16x32_bf16 v[44:47], v[130:133], v[186:189], v[44:47]
	v_mfma_f32_16x16x32_bf16 v[40:43], v[150:153], v[186:189], v[40:43]
	v_mfma_f32_16x16x32_bf16 v[28:31], v[130:133], v[194:197], v[28:31]
	v_mfma_f32_16x16x32_bf16 v[24:27], v[150:153], v[194:197], v[24:27]
	v_mfma_f32_16x16x32_bf16 v[12:15], v[130:133], v[202:205], v[12:15]
	v_mfma_f32_16x16x32_bf16 v[8:11], v[150:153], v[202:205], v[8:11]
	v_mfma_f32_16x16x32_bf16 v[60:63], v[134:137], v[182:185], v[60:63]
	v_mfma_f32_16x16x32_bf16 v[56:59], v[154:157], v[182:185], v[56:59]
	v_mfma_f32_16x16x32_bf16 v[44:47], v[134:137], v[190:193], v[44:47]
	v_mfma_f32_16x16x32_bf16 v[40:43], v[154:157], v[190:193], v[40:43]
	v_mfma_f32_16x16x32_bf16 v[28:31], v[134:137], v[198:201], v[28:31]
	v_mfma_f32_16x16x32_bf16 v[24:27], v[154:157], v[198:201], v[24:27]
	v_mfma_f32_16x16x32_bf16 v[12:15], v[134:137], v[206:209], v[12:15]
	v_mfma_f32_16x16x32_bf16 v[8:11], v[154:157], v[206:209], v[8:11]
	v_mfma_f32_16x16x32_bf16 v[52:55], v[158:161], v[174:177], v[52:55]
	v_mfma_f32_16x16x32_bf16 v[48:51], v[166:169], v[174:177], v[48:51]
	v_mfma_f32_16x16x32_bf16 v[36:39], v[158:161], v[186:189], v[36:39]
	v_mfma_f32_16x16x32_bf16 v[32:35], v[166:169], v[186:189], v[32:35]
	v_mfma_f32_16x16x32_bf16 v[20:23], v[158:161], v[194:197], v[20:23]
	v_mfma_f32_16x16x32_bf16 v[16:19], v[166:169], v[194:197], v[16:19]
	v_mfma_f32_16x16x32_bf16 v[4:7], v[158:161], v[202:205], v[4:7]
	v_mfma_f32_16x16x32_bf16 v[0:3], v[166:169], v[202:205], v[0:3]
	v_mfma_f32_16x16x32_bf16 v[52:55], v[162:165], v[182:185], v[52:55]
	v_mfma_f32_16x16x32_bf16 v[48:51], v[170:173], v[182:185], v[48:51]
	v_mfma_f32_16x16x32_bf16 v[36:39], v[162:165], v[190:193], v[36:39]
	v_mfma_f32_16x16x32_bf16 v[32:35], v[170:173], v[190:193], v[32:35]
	v_mfma_f32_16x16x32_bf16 v[20:23], v[162:165], v[198:201], v[20:23]
	v_mfma_f32_16x16x32_bf16 v[16:19], v[170:173], v[198:201], v[16:19]
	v_mfma_f32_16x16x32_bf16 v[4:7], v[162:165], v[206:209], v[4:7]
	v_mfma_f32_16x16x32_bf16 v[0:3], v[170:173], v[206:209], v[0:3]
	s_barrier
	s_add_i32 s73, s73, 2
	s_add_u32 s4, s4, 0x100
	s_addc_u32 s5, s5, 0
	s_add_u32 s69, s69, 0x100
	s_addc_u32 s72, s72, 0
	s_cmp_gt_u32 s73, 13
	s_cbranch_scc0 .LBB0_312
	s_setprio 0
	s_and_b64 vcc, exec, s[16:17]
	s_cbranch_vccz .LBB0_315
	s_barrier

.LBB0_588:
	s_mov_b32 s70, 0
	s_mov_b64 s[68:69], 0x100
	v_mov_b64_e32 v[98:99], v[142:143]
	v_mov_b64_e32 v[144:145], v[140:141]
	s_cmp_eq_u32 s34, 0
	s_cbranch_scc0 .Lsprio_skip1
	s_setprio 1
.Lsprio_skip1:
.LBB0_589:
	s_add_i32 s27, s70, 2
	s_add_u32 s30, s24, s68
	s_addc_u32 s31, s25, s69
	s_add_u32 s87, s22, s68
	s_addc_u32 s88, s23, s69
	s_add_i32 s89, 0, 0x10000
	s_cmp_eq_u32 s83, s70
	s_cselect_b32 s71, s7, s31
	s_cselect_b32 s70, s6, s30
	v_add_u32_e32 v96, s89, v146
	s_cselect_b32 s31, s67, s88
	s_cselect_b32 s30, s66, s87
	s_add_i32 s87, 0, 0x14000
	ds_read_b128 v[148:151], v96
	ds_read_b128 v[152:155], v96 offset:1024
	ds_read_b128 v[156:159], v96 offset:2048
	ds_read_b128 v[160:163], v96 offset:3072
	v_add_u32_e32 v96, s87, v146
	ds_read_b128 v[164:167], v96
	ds_read_b128 v[172:175], v96 offset:1024
	ds_read_b128 v[176:179], v96 offset:2048
	ds_read_b128 v[180:183], v96 offset:3072
	v_lshl_add_u64 v[168:169], s[24:25], 0, v[144:145]
	s_add_i32 m0, s76, 0xc000
	ds_read_b128 v[184:187], v147
	ds_read_b128 v[188:191], v147 offset:1024
	ds_read_b128 v[192:195], v147 offset:2048
	ds_read_b128 v[196:199], v147 offset:3072
	ds_read_b128 v[200:203], v147 offset:4096
	ds_read_b128 v[204:207], v147 offset:5120
	ds_read_b128 v[208:211], v147 offset:6144
	ds_read_b128 v[216:219], v147 offset:7168
	global_load_lds_dwordx4 v[168:169], off
	v_lshl_add_u64 v[168:169], s[24:25], 0, v[98:99]
	s_add_i32 m0, s76, 0xe000
	s_nop 0
	global_load_lds_dwordx4 v[168:169], off
	s_waitcnt vmcnt(8)
	s_waitcnt lgkmcnt(0)
	s_barrier
	s_waitcnt lgkmcnt(0)
	v_mfma_f32_16x16x32_bf16 v[128:131], v[148:151], v[184:187], v[128:131]
	v_mfma_f32_16x16x32_bf16 v[124:127], v[156:159], v[184:187], v[124:127]
	v_mfma_f32_16x16x32_bf16 v[112:115], v[148:151], v[192:195], v[112:115]
	v_mfma_f32_16x16x32_bf16 v[108:111], v[156:159], v[192:195], v[108:111]
	v_mfma_f32_16x16x32_bf16 v[92:95], v[148:151], v[200:203], v[92:95]
	v_mfma_f32_16x16x32_bf16 v[88:91], v[156:159], v[200:203], v[88:91]
	v_mfma_f32_16x16x32_bf16 v[76:79], v[148:151], v[208:211], v[76:79]
	v_mfma_f32_16x16x32_bf16 v[72:75], v[156:159], v[208:211], v[72:75]
	v_mfma_f32_16x16x32_bf16 v[128:131], v[152:155], v[188:191], v[128:131]
	v_mfma_f32_16x16x32_bf16 v[124:127], v[160:163], v[188:191], v[124:127]
	v_mfma_f32_16x16x32_bf16 v[112:115], v[152:155], v[196:199], v[112:115]
	v_mfma_f32_16x16x32_bf16 v[108:111], v[160:163], v[196:199], v[108:111]
	v_mfma_f32_16x16x32_bf16 v[92:95], v[152:155], v[204:207], v[92:95]
	v_mfma_f32_16x16x32_bf16 v[88:91], v[160:163], v[204:207], v[88:91]
	v_mfma_f32_16x16x32_bf16 v[76:79], v[152:155], v[216:219], v[76:79]
	v_mfma_f32_16x16x32_bf16 v[72:75], v[160:163], v[216:219], v[72:75]
	v_mfma_f32_16x16x32_bf16 v[120:123], v[164:167], v[184:187], v[120:123]
	v_mfma_f32_16x16x32_bf16 v[116:119], v[176:179], v[184:187], v[116:119]
	v_mfma_f32_16x16x32_bf16 v[104:107], v[164:167], v[192:195], v[104:107]
	v_mfma_f32_16x16x32_bf16 v[100:103], v[176:179], v[192:195], v[100:103]
	v_mfma_f32_16x16x32_bf16 v[84:87], v[164:167], v[200:203], v[84:87]
	v_mfma_f32_16x16x32_bf16 v[80:83], v[176:179], v[200:203], v[80:83]
	v_mfma_f32_16x16x32_bf16 v[68:71], v[164:167], v[208:211], v[68:71]
	v_mfma_f32_16x16x32_bf16 v[64:67], v[176:179], v[208:211], v[64:67]
	v_mfma_f32_16x16x32_bf16 v[120:123], v[172:175], v[188:191], v[120:123]
	v_mfma_f32_16x16x32_bf16 v[116:119], v[180:183], v[188:191], v[116:119]
	v_mfma_f32_16x16x32_bf16 v[104:107], v[172:175], v[196:199], v[104:107]
	v_mfma_f32_16x16x32_bf16 v[100:103], v[180:183], v[196:199], v[100:103]
	v_mfma_f32_16x16x32_bf16 v[84:87], v[172:175], v[204:207], v[84:87]
	v_mfma_f32_16x16x32_bf16 v[80:83], v[180:183], v[204:207], v[80:83]
	v_mfma_f32_16x16x32_bf16 v[68:71], v[172:175], v[216:219], v[68:71]
	v_mfma_f32_16x16x32_bf16 v[64:67], v[180:183], v[216:219], v[64:67]
	s_barrier
	s_add_i32 s88, s89, s73
	v_lshl_add_u64 v[168:169], s[30:31], 0, v[134:135]
	s_mov_b32 m0, s88
	ds_read_b128 v[184:187], v147 offset:16384
	ds_read_b128 v[188:191], v147 offset:17408
	ds_read_b128 v[192:195], v147 offset:18432
	ds_read_b128 v[196:199], v147 offset:19456
	ds_read_b128 v[200:203], v147 offset:20480
	ds_read_b128 v[204:207], v147 offset:21504
	ds_read_b128 v[208:211], v147 offset:22528
	ds_read_b128 v[216:219], v147 offset:23552
	global_load_lds_dwordx4 v[168:169], off
	s_add_i32 m0, s88, 0x2000
	v_lshl_add_u64 v[220:221], s[30:31], 0, v[138:139]
	s_add_u32 s30, s30, s63
	s_addc_u32 s31, s31, 0
	s_add_i32 s87, s87, s73
	global_load_lds_dwordx4 v[220:221], off
	v_lshl_add_u64 v[222:223], s[30:31], 0, v[134:135]
	s_mov_b32 m0, s87
	v_lshl_add_u64 v[224:225], s[30:31], 0, v[138:139]
	global_load_lds_dwordx4 v[222:223], off
	s_add_i32 m0, s87, 0x2000
	v_lshl_add_u64 v[226:227], s[70:71], 0, v[132:133]
	global_load_lds_dwordx4 v[224:225], off
	s_mov_b32 m0, s76
	v_lshl_add_u64 v[228:229], s[70:71], 0, v[136:137]
	global_load_lds_dwordx4 v[226:227], off
	s_mov_b32 m0, s77
	s_nop 0
	global_load_lds_dwordx4 v[228:229], off
	s_waitcnt vmcnt(8)
	s_waitcnt lgkmcnt(0)
	s_barrier
	s_waitcnt lgkmcnt(0)
	v_mfma_f32_16x16x32_bf16 v[60:63], v[148:151], v[184:187], v[60:63]
	v_mfma_f32_16x16x32_bf16 v[56:59], v[156:159], v[184:187], v[56:59]
	v_mfma_f32_16x16x32_bf16 v[44:47], v[148:151], v[192:195], v[44:47]
	v_mfma_f32_16x16x32_bf16 v[40:43], v[156:159], v[192:195], v[40:43]
	v_mfma_f32_16x16x32_bf16 v[28:31], v[148:151], v[200:203], v[28:31]
	v_mfma_f32_16x16x32_bf16 v[24:27], v[156:159], v[200:203], v[24:27]
	v_mfma_f32_16x16x32_bf16 v[12:15], v[148:151], v[208:211], v[12:15]
	v_mfma_f32_16x16x32_bf16 v[8:11], v[156:159], v[208:211], v[8:11]
	v_mfma_f32_16x16x32_bf16 v[60:63], v[152:155], v[188:191], v[60:63]
	v_mfma_f32_16x16x32_bf16 v[56:59], v[160:163], v[188:191], v[56:59]
	v_mfma_f32_16x16x32_bf16 v[44:47], v[152:155], v[196:199], v[44:47]
	v_mfma_f32_16x16x32_bf16 v[40:43], v[160:163], v[196:199], v[40:43]
	v_mfma_f32_16x16x32_bf16 v[28:31], v[152:155], v[204:207], v[28:31]
	v_mfma_f32_16x16x32_bf16 v[24:27], v[160:163], v[204:207], v[24:27]
	v_mfma_f32_16x16x32_bf16 v[12:15], v[152:155], v[216:219], v[12:15]
	v_mfma_f32_16x16x32_bf16 v[8:11], v[160:163], v[216:219], v[8:11]
	v_mfma_f32_16x16x32_bf16 v[52:55], v[164:167], v[184:187], v[52:55]
	v_mfma_f32_16x16x32_bf16 v[48:51], v[176:179], v[184:187], v[48:51]
	v_mfma_f32_16x16x32_bf16 v[36:39], v[164:167], v[192:195], v[36:39]
	v_mfma_f32_16x16x32_bf16 v[32:35], v[176:179], v[192:195], v[32:35]
	v_mfma_f32_16x16x32_bf16 v[20:23], v[164:167], v[200:203], v[20:23]
	v_mfma_f32_16x16x32_bf16 v[16:19], v[176:179], v[200:203], v[16:19]
	v_mfma_f32_16x16x32_bf16 v[4:7], v[164:167], v[208:211], v[4:7]
	v_mfma_f32_16x16x32_bf16 v[0:3], v[176:179], v[208:211], v[0:3]
	v_mfma_f32_16x16x32_bf16 v[52:55], v[172:175], v[188:191], v[52:55]
	v_mfma_f32_16x16x32_bf16 v[48:51], v[180:183], v[188:191], v[48:51]
	v_mfma_f32_16x16x32_bf16 v[36:39], v[172:175], v[196:199], v[36:39]
	v_mfma_f32_16x16x32_bf16 v[32:35], v[180:183], v[196:199], v[32:35]
	v_mfma_f32_16x16x32_bf16 v[20:23], v[172:175], v[204:207], v[20:23]
	v_mfma_f32_16x16x32_bf16 v[16:19], v[180:183], v[204:207], v[16:19]
	v_mfma_f32_16x16x32_bf16 v[4:7], v[172:175], v[216:219], v[4:7]
	v_mfma_f32_16x16x32_bf16 v[0:3], v[180:183], v[216:219], v[0:3]
	s_barrier
	s_add_i32 s87, 0, 0x18000
	v_add_u32_e32 v96, s87, v146
	s_add_i32 s88, 0, 0x1c000
	ds_read_b128 v[148:151], v96
	ds_read_b128 v[152:155], v96 offset:1024
	ds_read_b128 v[156:159], v96 offset:2048
	ds_read_b128 v[160:163], v96 offset:3072
	v_add_u32_e32 v96, s88, v146
	ds_read_b128 v[164:167], v96
	ds_read_b128 v[172:175], v96 offset:1024
	ds_read_b128 v[176:179], v96 offset:2048
	ds_read_b128 v[180:183], v96 offset:3072
	s_add_u32 s30, s70, 0x40000
	s_addc_u32 s31, s71, 0
	s_mov_b32 m0, s78
	v_lshl_add_u64 v[230:231], s[30:31], 0, v[132:133]
	ds_read_b128 v[184:187], v147 offset:32768
	ds_read_b128 v[188:191], v147 offset:33792
	ds_read_b128 v[192:195], v147 offset:34816
	ds_read_b128 v[196:199], v147 offset:35840
	ds_read_b128 v[200:203], v147 offset:36864
	ds_read_b128 v[204:207], v147 offset:37888
	ds_read_b128 v[208:211], v147 offset:38912
	ds_read_b128 v[216:219], v147 offset:39936
	global_load_lds_dwordx4 v[230:231], off
	v_lshl_add_u64 v[230:231], s[30:31], 0, v[136:137]
	s_mov_b32 m0, s79
	s_nop 0
	global_load_lds_dwordx4 v[230:231], off
	s_waitcnt vmcnt(8)
	s_waitcnt lgkmcnt(0)
	s_barrier
	s_waitcnt lgkmcnt(0)
	v_mfma_f32_16x16x32_bf16 v[128:131], v[148:151], v[184:187], v[128:131]
	v_mfma_f32_16x16x32_bf16 v[124:127], v[156:159], v[184:187], v[124:127]
	v_mfma_f32_16x16x32_bf16 v[112:115], v[148:151], v[192:195], v[112:115]
	v_mfma_f32_16x16x32_bf16 v[108:111], v[156:159], v[192:195], v[108:111]
	v_mfma_f32_16x16x32_bf16 v[92:95], v[148:151], v[200:203], v[92:95]
	v_mfma_f32_16x16x32_bf16 v[88:91], v[156:159], v[200:203], v[88:91]
	v_mfma_f32_16x16x32_bf16 v[76:79], v[148:151], v[208:211], v[76:79]
	v_mfma_f32_16x16x32_bf16 v[72:75], v[156:159], v[208:211], v[72:75]
	v_mfma_f32_16x16x32_bf16 v[128:131], v[152:155], v[188:191], v[128:131]
	v_mfma_f32_16x16x32_bf16 v[124:127], v[160:163], v[188:191], v[124:127]
	v_mfma_f32_16x16x32_bf16 v[112:115], v[152:155], v[196:199], v[112:115]
	v_mfma_f32_16x16x32_bf16 v[108:111], v[160:163], v[196:199], v[108:111]
	v_mfma_f32_16x16x32_bf16 v[92:95], v[152:155], v[204:207], v[92:95]
	v_mfma_f32_16x16x32_bf16 v[88:91], v[160:163], v[204:207], v[88:91]
	v_mfma_f32_16x16x32_bf16 v[76:79], v[152:155], v[216:219], v[76:79]
	v_mfma_f32_16x16x32_bf16 v[72:75], v[160:163], v[216:219], v[72:75]
	v_mfma_f32_16x16x32_bf16 v[120:123], v[164:167], v[184:187], v[120:123]
	v_mfma_f32_16x16x32_bf16 v[116:119], v[176:179], v[184:187], v[116:119]
	v_mfma_f32_16x16x32_bf16 v[104:107], v[164:167], v[192:195], v[104:107]
	v_mfma_f32_16x16x32_bf16 v[100:103], v[176:179], v[192:195], v[100:103]
	v_mfma_f32_16x16x32_bf16 v[84:87], v[164:167], v[200:203], v[84:87]
	v_mfma_f32_16x16x32_bf16 v[80:83], v[176:179], v[200:203], v[80:83]
	v_mfma_f32_16x16x32_bf16 v[68:71], v[164:167], v[208:211], v[68:71]
	v_mfma_f32_16x16x32_bf16 v[64:67], v[176:179], v[208:211], v[64:67]
	v_mfma_f32_16x16x32_bf16 v[120:123], v[172:175], v[188:191], v[120:123]
	v_mfma_f32_16x16x32_bf16 v[116:119], v[180:183], v[188:191], v[116:119]
	v_mfma_f32_16x16x32_bf16 v[104:107], v[172:175], v[196:199], v[104:107]
	v_mfma_f32_16x16x32_bf16 v[100:103], v[180:183], v[196:199], v[100:103]
	v_mfma_f32_16x16x32_bf16 v[84:87], v[172:175], v[204:207], v[84:87]
	v_mfma_f32_16x16x32_bf16 v[80:83], v[180:183], v[204:207], v[80:83]
	v_mfma_f32_16x16x32_bf16 v[68:71], v[172:175], v[216:219], v[68:71]
	v_mfma_f32_16x16x32_bf16 v[64:67], v[180:183], v[216:219], v[64:67]
	s_barrier
	s_add_i32 s30, s87, s73
	v_lshl_add_u64 v[168:169], v[168:169], 0, s[48:49]
	s_mov_b32 m0, s30
	ds_read_b128 v[184:187], v147 offset:49152
	ds_read_b128 v[188:191], v147 offset:50176
	ds_read_b128 v[192:195], v147 offset:51200
	ds_read_b128 v[196:199], v147 offset:52224
	ds_read_b128 v[200:203], v147 offset:53248
	ds_read_b128 v[204:207], v147 offset:54272
	ds_read_b128 v[208:211], v147 offset:55296
	ds_read_b128 v[216:219], v147 offset:56320
	global_load_lds_dwordx4 v[168:169], off
	v_lshl_add_u64 v[168:169], v[220:221], 0, s[48:49]
	s_add_i32 m0, s30, 0x2000
	s_add_i32 s30, s88, s73
	global_load_lds_dwordx4 v[168:169], off
	v_lshl_add_u64 v[168:169], v[222:223], 0, s[48:49]
	s_mov_b32 m0, s30
	s_nop 0
	global_load_lds_dwordx4 v[168:169], off
	v_lshl_add_u64 v[168:169], v[224:225], 0, s[48:49]
	s_add_i32 m0, s30, 0x2000
	s_nop 0
	global_load_lds_dwordx4 v[168:169], off
	v_lshl_add_u64 v[168:169], v[226:227], 0, s[48:49]
	s_mov_b32 m0, s80
	s_nop 0
	global_load_lds_dwordx4 v[168:169], off
	v_lshl_add_u64 v[168:169], v[228:229], 0, s[48:49]
	s_mov_b32 m0, s81
	s_nop 0
	global_load_lds_dwordx4 v[168:169], off
	s_waitcnt vmcnt(8)
	s_waitcnt lgkmcnt(0)
	s_barrier
	s_waitcnt lgkmcnt(0)
	v_mfma_f32_16x16x32_bf16 v[60:63], v[148:151], v[184:187], v[60:63]
	v_mfma_f32_16x16x32_bf16 v[56:59], v[156:159], v[184:187], v[56:59]
	v_mfma_f32_16x16x32_bf16 v[44:47], v[148:151], v[192:195], v[44:47]
	v_mfma_f32_16x16x32_bf16 v[40:43], v[156:159], v[192:195], v[40:43]
	v_mfma_f32_16x16x32_bf16 v[28:31], v[148:151], v[200:203], v[28:31]
	v_mfma_f32_16x16x32_bf16 v[24:27], v[156:159], v[200:203], v[24:27]
	v_mfma_f32_16x16x32_bf16 v[12:15], v[148:151], v[208:211], v[12:15]
	v_mfma_f32_16x16x32_bf16 v[8:11], v[156:159], v[208:211], v[8:11]
	v_mfma_f32_16x16x32_bf16 v[60:63], v[152:155], v[188:191], v[60:63]
	v_mfma_f32_16x16x32_bf16 v[56:59], v[160:163], v[188:191], v[56:59]
	v_mfma_f32_16x16x32_bf16 v[44:47], v[152:155], v[196:199], v[44:47]
	v_mfma_f32_16x16x32_bf16 v[40:43], v[160:163], v[196:199], v[40:43]
	v_mfma_f32_16x16x32_bf16 v[28:31], v[152:155], v[204:207], v[28:31]
	v_mfma_f32_16x16x32_bf16 v[24:27], v[160:163], v[204:207], v[24:27]
	v_mfma_f32_16x16x32_bf16 v[12:15], v[152:155], v[216:219], v[12:15]
	v_mfma_f32_16x16x32_bf16 v[8:11], v[160:163], v[216:219], v[8:11]
	v_mfma_f32_16x16x32_bf16 v[52:55], v[164:167], v[184:187], v[52:55]
	v_mfma_f32_16x16x32_bf16 v[48:51], v[176:179], v[184:187], v[48:51]
	v_mfma_f32_16x16x32_bf16 v[36:39], v[164:167], v[192:195], v[36:39]
	v_mfma_f32_16x16x32_bf16 v[32:35], v[176:179], v[192:195], v[32:35]
	v_mfma_f32_16x16x32_bf16 v[20:23], v[164:167], v[200:203], v[20:23]
	v_mfma_f32_16x16x32_bf16 v[16:19], v[176:179], v[200:203], v[16:19]
	v_mfma_f32_16x16x32_bf16 v[4:7], v[164:167], v[208:211], v[4:7]
	v_mfma_f32_16x16x32_bf16 v[0:3], v[176:179], v[208:211], v[0:3]
	v_mfma_f32_16x16x32_bf16 v[52:55], v[172:175], v[188:191], v[52:55]
	v_mfma_f32_16x16x32_bf16 v[48:51], v[180:183], v[188:191], v[48:51]
	v_mfma_f32_16x16x32_bf16 v[36:39], v[172:175], v[196:199], v[36:39]
	v_mfma_f32_16x16x32_bf16 v[32:35], v[180:183], v[196:199], v[32:35]
	v_mfma_f32_16x16x32_bf16 v[20:23], v[172:175], v[204:207], v[20:23]
	v_mfma_f32_16x16x32_bf16 v[16:19], v[180:183], v[204:207], v[16:19]
	v_mfma_f32_16x16x32_bf16 v[4:7], v[172:175], v[216:219], v[4:7]
	v_mfma_f32_16x16x32_bf16 v[0:3], v[180:183], v[216:219], v[0:3]
	s_barrier
	s_add_u32 s68, s68, 0x100
	s_addc_u32 s69, s69, 0
	v_lshl_add_u64 v[144:145], v[144:145], 0, s[52:53]
	v_lshl_add_u64 v[98:99], v[98:99], 0, s[52:53]
	s_cmp_ge_u32 s27, s82
	s_mov_b32 s70, s27
	s_cbranch_scc0 .LBB0_589
	s_setprio 0
	s_and_b64 vcc, exec, s[4:5]
	s_cbranch_vccnz .LBB0_577
	v_mov_b32_e32 v96, v97
	v_mov_b32_e32 v98, v97
	v_mov_b32_e32 v99, v97
	v_mov_b64_e32 v[0:1], v[96:97]
	v_mov_b64_e32 v[4:5], v[96:97]
	v_mov_b64_e32 v[16:17], v[96:97]
	v_mov_b64_e32 v[20:21], v[96:97]
	v_mov_b64_e32 v[32:33], v[96:97]
	v_mov_b64_e32 v[36:37], v[96:97]
	v_mov_b64_e32 v[48:49], v[96:97]
	v_mov_b64_e32 v[52:53], v[96:97]
	v_mov_b64_e32 v[8:9], v[96:97]
	v_mov_b64_e32 v[12:13], v[96:97]
	v_mov_b64_e32 v[24:25], v[96:97]
	v_mov_b64_e32 v[28:29], v[96:97]
	v_mov_b64_e32 v[40:41], v[96:97]
	v_mov_b64_e32 v[44:45], v[96:97]
	v_mov_b64_e32 v[56:57], v[96:97]
	v_mov_b64_e32 v[60:61], v[96:97]
	v_mov_b64_e32 v[64:65], v[96:97]
	v_mov_b64_e32 v[68:69], v[96:97]
	v_mov_b64_e32 v[80:81], v[96:97]
	v_mov_b64_e32 v[84:85], v[96:97]
	v_mov_b64_e32 v[102:103], v[98:99]
	v_mov_b64_e32 v[106:107], v[98:99]
	v_mov_b64_e32 v[118:119], v[98:99]
	v_mov_b64_e32 v[122:123], v[98:99]
	v_mov_b64_e32 v[72:73], v[96:97]
	v_mov_b64_e32 v[76:77], v[96:97]
	v_mov_b64_e32 v[88:89], v[96:97]
	v_mov_b64_e32 v[92:93], v[96:97]
	v_mov_b64_e32 v[110:111], v[98:99]
	v_mov_b64_e32 v[114:115], v[98:99]
	v_mov_b64_e32 v[126:127], v[98:99]
	v_mov_b64_e32 v[130:131], v[98:99]
	v_mov_b64_e32 v[2:3], v[98:99]
	v_mov_b64_e32 v[6:7], v[98:99]
	v_mov_b64_e32 v[18:19], v[98:99]
	v_mov_b64_e32 v[22:23], v[98:99]
	v_mov_b64_e32 v[34:35], v[98:99]
	v_mov_b64_e32 v[38:39], v[98:99]
	v_mov_b64_e32 v[50:51], v[98:99]
	v_mov_b64_e32 v[54:55], v[98:99]
	v_mov_b64_e32 v[10:11], v[98:99]
	v_mov_b64_e32 v[14:15], v[98:99]
	v_mov_b64_e32 v[26:27], v[98:99]
	v_mov_b64_e32 v[30:31], v[98:99]
	v_mov_b64_e32 v[42:43], v[98:99]
	v_mov_b64_e32 v[46:47], v[98:99]
	v_mov_b64_e32 v[58:59], v[98:99]
	v_mov_b64_e32 v[62:63], v[98:99]
	v_mov_b64_e32 v[66:67], v[98:99]
	v_mov_b64_e32 v[70:71], v[98:99]
	v_mov_b64_e32 v[82:83], v[98:99]
	v_mov_b64_e32 v[86:87], v[98:99]
	v_mov_b64_e32 v[100:101], v[96:97]
	v_mov_b64_e32 v[104:105], v[96:97]
	v_mov_b64_e32 v[116:117], v[96:97]
	v_mov_b64_e32 v[120:121], v[96:97]
	v_mov_b64_e32 v[74:75], v[98:99]
	v_mov_b64_e32 v[78:79], v[98:99]
	v_mov_b64_e32 v[90:91], v[98:99]
	v_mov_b64_e32 v[94:95], v[98:99]
	v_mov_b64_e32 v[108:109], v[96:97]
	v_mov_b64_e32 v[112:113], v[96:97]
	v_mov_b64_e32 v[124:125], v[96:97]
	v_mov_b64_e32 v[128:129], v[96:97]
	s_mov_b32 s14, s85
	s_mov_b32 s18, s26
	s_mov_b64 s[22:23], s[66:67]
	s_mov_b64 s[24:25], s[6:7]
	s_mov_b32 s84, s86
	s_branch .LBB0_577

.LBB0_732:
	s_ashr_i32 s19, s18, 31
	s_lshl_b64 s[20:21], s[18:19], 19
	s_add_u32 s20, s70, s20
	s_addc_u32 s21, s71, s21
	s_and_b64 s[22:23], s[2:3], exec
	s_cselect_b32 s19, s21, s27
	s_cselect_b32 s35, s20, s26
	s_ashr_i32 s17, s16, 31
	s_lshl_b64 s[22:23], s[16:17], 19
	s_add_u32 s22, s72, s22
	s_addc_u32 s23, s73, s23
	s_and_b64 s[30:31], s[2:3], exec
	s_cselect_b32 s17, s23, s67
	s_cselect_b32 s83, s22, s66
	s_add_u32 s26, s26, 0x40080
	s_addc_u32 s27, s27, 0
	s_add_u32 s84, s66, 0x100
	v_mov_b32_e32 v0, 0
	s_addc_u32 s85, s67, 0
	s_mov_b32 s86, -2
	v_mov_b32_e32 v1, v0
	v_mov_b32_e32 v2, v0
	v_mov_b32_e32 v3, v0
	v_mov_b32_e32 v4, v0
	v_mov_b32_e32 v5, v0
	v_mov_b32_e32 v6, v0
	v_mov_b32_e32 v7, v0
	v_mov_b32_e32 v16, v0
	v_mov_b32_e32 v17, v0
	v_mov_b32_e32 v18, v0
	v_mov_b32_e32 v19, v0
	v_mov_b32_e32 v20, v0
	v_mov_b32_e32 v21, v0
	v_mov_b32_e32 v22, v0
	v_mov_b32_e32 v23, v0
	v_mov_b32_e32 v32, v0
	v_mov_b32_e32 v33, v0
	v_mov_b32_e32 v34, v0
	v_mov_b32_e32 v35, v0
	v_mov_b32_e32 v36, v0
	v_mov_b32_e32 v37, v0
	v_mov_b32_e32 v38, v0
	v_mov_b32_e32 v39, v0
	v_mov_b32_e32 v48, v0
	v_mov_b32_e32 v49, v0
	v_mov_b32_e32 v50, v0
	v_mov_b32_e32 v51, v0
	v_mov_b32_e32 v52, v0
	v_mov_b32_e32 v53, v0
	v_mov_b32_e32 v54, v0
	v_mov_b32_e32 v55, v0
	v_mov_b32_e32 v8, v0
	v_mov_b32_e32 v9, v0
	v_mov_b32_e32 v10, v0
	v_mov_b32_e32 v11, v0
	v_mov_b32_e32 v12, v0
	v_mov_b32_e32 v13, v0
	v_mov_b32_e32 v14, v0
	v_mov_b32_e32 v15, v0
	v_mov_b32_e32 v24, v0
	v_mov_b32_e32 v25, v0
	v_mov_b32_e32 v26, v0
	v_mov_b32_e32 v27, v0
	v_mov_b32_e32 v28, v0
	v_mov_b32_e32 v29, v0
	v_mov_b32_e32 v30, v0
	v_mov_b32_e32 v31, v0
	v_mov_b32_e32 v40, v0
	v_mov_b32_e32 v41, v0
	v_mov_b32_e32 v42, v0
	v_mov_b32_e32 v43, v0
	v_mov_b32_e32 v44, v0
	v_mov_b32_e32 v45, v0
	v_mov_b32_e32 v46, v0
	v_mov_b32_e32 v47, v0
	v_mov_b32_e32 v56, v0
	v_mov_b32_e32 v57, v0
	v_mov_b32_e32 v58, v0
	v_mov_b32_e32 v59, v0
	v_mov_b32_e32 v60, v0
	v_mov_b32_e32 v61, v0
	v_mov_b32_e32 v62, v0
	v_mov_b32_e32 v63, v0
	v_mov_b32_e32 v64, v0
	v_mov_b32_e32 v65, v0
	v_mov_b32_e32 v66, v0
	v_mov_b32_e32 v67, v0
	v_mov_b32_e32 v68, v0
	v_mov_b32_e32 v69, v0
	v_mov_b32_e32 v70, v0
	v_mov_b32_e32 v71, v0
	v_mov_b32_e32 v80, v0
	v_mov_b32_e32 v81, v0
	v_mov_b32_e32 v82, v0
	v_mov_b32_e32 v83, v0
	v_mov_b32_e32 v84, v0
	v_mov_b32_e32 v85, v0
	v_mov_b32_e32 v86, v0
	v_mov_b32_e32 v87, v0
	v_mov_b32_e32 v98, v0
	v_mov_b32_e32 v99, v0
	v_mov_b32_e32 v100, v0
	v_mov_b32_e32 v101, v0
	v_mov_b32_e32 v102, v0
	v_mov_b32_e32 v103, v0
	v_mov_b32_e32 v104, v0
	v_mov_b32_e32 v105, v0
	v_mov_b32_e32 v114, v0
	v_mov_b32_e32 v115, v0
	v_mov_b32_e32 v116, v0
	v_mov_b32_e32 v117, v0
	v_mov_b32_e32 v118, v0
	v_mov_b32_e32 v119, v0
	v_mov_b32_e32 v120, v0
	v_mov_b32_e32 v121, v0
	v_mov_b32_e32 v72, v0
	v_mov_b32_e32 v73, v0
	v_mov_b32_e32 v74, v0
	v_mov_b32_e32 v75, v0
	v_mov_b32_e32 v76, v0
	v_mov_b32_e32 v77, v0
	v_mov_b32_e32 v78, v0
	v_mov_b32_e32 v79, v0
	v_mov_b32_e32 v88, v0
	v_mov_b32_e32 v89, v0
	v_mov_b32_e32 v90, v0
	v_mov_b32_e32 v91, v0
	v_mov_b32_e32 v92, v0
	v_mov_b32_e32 v93, v0
	v_mov_b32_e32 v94, v0
	v_mov_b32_e32 v95, v0
	v_mov_b32_e32 v106, v0
	v_mov_b32_e32 v107, v0
	v_mov_b32_e32 v108, v0
	v_mov_b32_e32 v109, v0
	v_mov_b32_e32 v110, v0
	v_mov_b32_e32 v111, v0
	v_mov_b32_e32 v112, v0
	v_mov_b32_e32 v113, v0
	v_mov_b32_e32 v122, v0
	v_mov_b32_e32 v123, v0
	v_mov_b32_e32 v124, v0
	v_mov_b32_e32 v125, v0
	v_mov_b32_e32 v126, v0
	v_mov_b32_e32 v127, v0
	v_mov_b32_e32 v128, v0
	v_mov_b32_e32 v129, v0
	s_cmp_eq_u32 s62, 0
	s_cbranch_scc0 .Lsprio_skip2
	s_setprio 1
.Lsprio_skip2:
.LBB0_733:
	s_add_u32 s30, s26, 0xfffc0080
	s_addc_u32 s31, s27, -1
	s_add_i32 s87, 0, 0x10000
	s_cmp_eq_u32 s86, 12
	s_cselect_b32 s69, s19, s31
	s_cselect_b32 s68, s35, s30
	s_cselect_b32 s67, s17, s85
	s_cselect_b32 s66, s83, s84
	s_add_i32 s88, 0, 0x14000
	v_add_u32_e32 v156, s87, v146
	v_add_u32_e32 v172, s88, v146
	ds_read_b128 v[140:143], v156
	ds_read_b128 v[148:151], v156 offset:1024
	ds_read_b128 v[152:155], v156 offset:2048
	ds_read_b128 v[156:159], v156 offset:3072
	ds_read_b128 v[160:163], v172
	ds_read_b128 v[164:167], v172 offset:1024
	ds_read_b128 v[168:171], v172 offset:2048
	ds_read_b128 v[172:175], v172 offset:3072
	v_lshl_add_u64 v[208:209], s[26:27], 0, v[136:137]
	s_add_i32 m0, s75, 0xc000
	ds_read_b128 v[176:179], v147
	ds_read_b128 v[180:183], v147 offset:1024
	ds_read_b128 v[184:187], v147 offset:2048
	ds_read_b128 v[188:191], v147 offset:3072
	ds_read_b128 v[192:195], v147 offset:4096
	ds_read_b128 v[196:199], v147 offset:5120
	ds_read_b128 v[200:203], v147 offset:6144
	ds_read_b128 v[204:207], v147 offset:7168
	global_load_lds_dwordx4 v[208:209], off
	v_lshl_add_u64 v[208:209], s[26:27], 0, v[138:139]
	s_add_i32 m0, s75, 0xe000
	s_nop 0
	global_load_lds_dwordx4 v[208:209], off
	s_waitcnt vmcnt(8)
	s_waitcnt lgkmcnt(0)
	s_barrier
	s_waitcnt lgkmcnt(0)
	v_mfma_f32_16x16x32_bf16 v[126:129], v[140:143], v[176:179], v[126:129]
	v_mfma_f32_16x16x32_bf16 v[122:125], v[152:155], v[176:179], v[122:125]
	v_mfma_f32_16x16x32_bf16 v[110:113], v[140:143], v[184:187], v[110:113]
	v_mfma_f32_16x16x32_bf16 v[106:109], v[152:155], v[184:187], v[106:109]
	v_mfma_f32_16x16x32_bf16 v[92:95], v[140:143], v[192:195], v[92:95]
	v_mfma_f32_16x16x32_bf16 v[88:91], v[152:155], v[192:195], v[88:91]
	v_mfma_f32_16x16x32_bf16 v[76:79], v[140:143], v[200:203], v[76:79]
	v_mfma_f32_16x16x32_bf16 v[72:75], v[152:155], v[200:203], v[72:75]
	v_mfma_f32_16x16x32_bf16 v[126:129], v[148:151], v[180:183], v[126:129]
	v_mfma_f32_16x16x32_bf16 v[122:125], v[156:159], v[180:183], v[122:125]
	v_mfma_f32_16x16x32_bf16 v[110:113], v[148:151], v[188:191], v[110:113]
	v_mfma_f32_16x16x32_bf16 v[106:109], v[156:159], v[188:191], v[106:109]
	v_mfma_f32_16x16x32_bf16 v[92:95], v[148:151], v[196:199], v[92:95]
	v_mfma_f32_16x16x32_bf16 v[88:91], v[156:159], v[196:199], v[88:91]
	v_mfma_f32_16x16x32_bf16 v[76:79], v[148:151], v[204:207], v[76:79]
	v_mfma_f32_16x16x32_bf16 v[72:75], v[156:159], v[204:207], v[72:75]
	v_mfma_f32_16x16x32_bf16 v[118:121], v[160:163], v[176:179], v[118:121]
	v_mfma_f32_16x16x32_bf16 v[114:117], v[168:171], v[176:179], v[114:117]
	v_mfma_f32_16x16x32_bf16 v[102:105], v[160:163], v[184:187], v[102:105]
	v_mfma_f32_16x16x32_bf16 v[98:101], v[168:171], v[184:187], v[98:101]
	v_mfma_f32_16x16x32_bf16 v[84:87], v[160:163], v[192:195], v[84:87]
	v_mfma_f32_16x16x32_bf16 v[80:83], v[168:171], v[192:195], v[80:83]
	v_mfma_f32_16x16x32_bf16 v[68:71], v[160:163], v[200:203], v[68:71]
	v_mfma_f32_16x16x32_bf16 v[64:67], v[168:171], v[200:203], v[64:67]
	v_mfma_f32_16x16x32_bf16 v[118:121], v[164:167], v[180:183], v[118:121]
	v_mfma_f32_16x16x32_bf16 v[114:117], v[172:175], v[180:183], v[114:117]
	v_mfma_f32_16x16x32_bf16 v[102:105], v[164:167], v[188:191], v[102:105]
	v_mfma_f32_16x16x32_bf16 v[98:101], v[172:175], v[188:191], v[98:101]
	v_mfma_f32_16x16x32_bf16 v[84:87], v[164:167], v[196:199], v[84:87]
	v_mfma_f32_16x16x32_bf16 v[80:83], v[172:175], v[196:199], v[80:83]
	v_mfma_f32_16x16x32_bf16 v[68:71], v[164:167], v[204:207], v[68:71]
	v_mfma_f32_16x16x32_bf16 v[64:67], v[172:175], v[204:207], v[64:67]
	s_barrier
	s_add_i32 s30, s87, s63
	v_lshl_add_u64 v[208:209], s[66:67], 0, v[96:97]
	s_mov_b32 m0, s30
	ds_read_b128 v[176:179], v147 offset:16384
	ds_read_b128 v[180:183], v147 offset:17408
	ds_read_b128 v[184:187], v147 offset:18432
	ds_read_b128 v[188:191], v147 offset:19456
	ds_read_b128 v[192:195], v147 offset:20480
	ds_read_b128 v[196:199], v147 offset:21504
	ds_read_b128 v[200:203], v147 offset:22528
	ds_read_b128 v[204:207], v147 offset:23552
	global_load_lds_dwordx4 v[208:209], off
	s_add_i32 m0, s30, 0x2000
	s_add_u32 s30, s66, 0x40000
	v_lshl_add_u64 v[210:211], s[66:67], 0, v[130:131]
	s_addc_u32 s31, s67, 0
	s_add_i32 s87, s88, s63
	global_load_lds_dwordx4 v[210:211], off
	v_lshl_add_u64 v[216:217], s[30:31], 0, v[96:97]
	s_mov_b32 m0, s87
	v_lshl_add_u64 v[218:219], s[68:69], 0, v[132:133]
	global_load_lds_dwordx4 v[216:217], off
	v_lshl_add_u64 v[216:217], s[30:31], 0, v[130:131]
	s_add_i32 m0, s87, 0x2000
	s_nop 0
	global_load_lds_dwordx4 v[216:217], off
	v_lshl_add_u64 v[216:217], s[68:69], 0, v[134:135]
	s_mov_b32 m0, s75
	s_nop 0
	global_load_lds_dwordx4 v[216:217], off
	s_mov_b32 m0, s76
	s_nop 0
	global_load_lds_dwordx4 v[218:219], off
	s_waitcnt vmcnt(8)
	s_waitcnt lgkmcnt(0)
	s_barrier
	s_waitcnt lgkmcnt(0)
	v_mfma_f32_16x16x32_bf16 v[60:63], v[140:143], v[176:179], v[60:63]
	v_mfma_f32_16x16x32_bf16 v[56:59], v[152:155], v[176:179], v[56:59]
	v_mfma_f32_16x16x32_bf16 v[44:47], v[140:143], v[184:187], v[44:47]
	v_mfma_f32_16x16x32_bf16 v[40:43], v[152:155], v[184:187], v[40:43]
	v_mfma_f32_16x16x32_bf16 v[28:31], v[140:143], v[192:195], v[28:31]
	v_mfma_f32_16x16x32_bf16 v[24:27], v[152:155], v[192:195], v[24:27]
	v_mfma_f32_16x16x32_bf16 v[12:15], v[140:143], v[200:203], v[12:15]
	v_mfma_f32_16x16x32_bf16 v[8:11], v[152:155], v[200:203], v[8:11]
	v_mfma_f32_16x16x32_bf16 v[60:63], v[148:151], v[180:183], v[60:63]
	v_mfma_f32_16x16x32_bf16 v[56:59], v[156:159], v[180:183], v[56:59]
	v_mfma_f32_16x16x32_bf16 v[44:47], v[148:151], v[188:191], v[44:47]
	v_mfma_f32_16x16x32_bf16 v[40:43], v[156:159], v[188:191], v[40:43]
	v_mfma_f32_16x16x32_bf16 v[28:31], v[148:151], v[196:199], v[28:31]
	v_mfma_f32_16x16x32_bf16 v[24:27], v[156:159], v[196:199], v[24:27]
	v_mfma_f32_16x16x32_bf16 v[12:15], v[148:151], v[204:207], v[12:15]
	v_mfma_f32_16x16x32_bf16 v[8:11], v[156:159], v[204:207], v[8:11]
	v_mfma_f32_16x16x32_bf16 v[52:55], v[160:163], v[176:179], v[52:55]
	v_mfma_f32_16x16x32_bf16 v[48:51], v[168:171], v[176:179], v[48:51]
	v_mfma_f32_16x16x32_bf16 v[36:39], v[160:163], v[184:187], v[36:39]
	v_mfma_f32_16x16x32_bf16 v[32:35], v[168:171], v[184:187], v[32:35]
	v_mfma_f32_16x16x32_bf16 v[20:23], v[160:163], v[192:195], v[20:23]
	v_mfma_f32_16x16x32_bf16 v[16:19], v[168:171], v[192:195], v[16:19]
	v_mfma_f32_16x16x32_bf16 v[4:7], v[160:163], v[200:203], v[4:7]
	v_mfma_f32_16x16x32_bf16 v[0:3], v[168:171], v[200:203], v[0:3]
	v_mfma_f32_16x16x32_bf16 v[52:55], v[164:167], v[180:183], v[52:55]
	v_mfma_f32_16x16x32_bf16 v[48:51], v[172:175], v[180:183], v[48:51]
	v_mfma_f32_16x16x32_bf16 v[36:39], v[164:167], v[188:191], v[36:39]
	v_mfma_f32_16x16x32_bf16 v[32:35], v[172:175], v[188:191], v[32:35]
	v_mfma_f32_16x16x32_bf16 v[20:23], v[164:167], v[196:199], v[20:23]
	v_mfma_f32_16x16x32_bf16 v[16:19], v[172:175], v[196:199], v[16:19]
	v_mfma_f32_16x16x32_bf16 v[4:7], v[164:167], v[204:207], v[4:7]
	v_mfma_f32_16x16x32_bf16 v[0:3], v[172:175], v[204:207], v[0:3]
	s_barrier
	s_add_i32 s87, 0, 0x18000
	s_add_i32 s88, 0, 0x1c000
	v_add_u32_e32 v156, s87, v146
	v_add_u32_e32 v172, s88, v146
	ds_read_b128 v[140:143], v156
	ds_read_b128 v[148:151], v156 offset:1024
	ds_read_b128 v[152:155], v156 offset:2048
	ds_read_b128 v[156:159], v156 offset:3072
	ds_read_b128 v[160:163], v172
	ds_read_b128 v[164:167], v172 offset:1024
	ds_read_b128 v[168:171], v172 offset:2048
	ds_read_b128 v[172:175], v172 offset:3072
	s_add_u32 s30, s68, 0x40000
	s_addc_u32 s31, s69, 0
	s_mov_b32 m0, s77
	v_lshl_add_u64 v[220:221], s[30:31], 0, v[134:135]
	ds_read_b128 v[176:179], v147 offset:32768
	ds_read_b128 v[180:183], v147 offset:33792
	ds_read_b128 v[184:187], v147 offset:34816
	ds_read_b128 v[188:191], v147 offset:35840
	ds_read_b128 v[192:195], v147 offset:36864
	ds_read_b128 v[196:199], v147 offset:37888
	ds_read_b128 v[200:203], v147 offset:38912
	ds_read_b128 v[204:207], v147 offset:39936
	global_load_lds_dwordx4 v[220:221], off
	v_lshl_add_u64 v[220:221], s[30:31], 0, v[132:133]
	s_mov_b32 m0, s78
	s_nop 0
	global_load_lds_dwordx4 v[220:221], off
	s_waitcnt vmcnt(8)
	s_waitcnt lgkmcnt(0)
	s_barrier
	s_waitcnt lgkmcnt(0)
	v_mfma_f32_16x16x32_bf16 v[126:129], v[140:143], v[176:179], v[126:129]
	v_mfma_f32_16x16x32_bf16 v[122:125], v[152:155], v[176:179], v[122:125]
	v_mfma_f32_16x16x32_bf16 v[110:113], v[140:143], v[184:187], v[110:113]
	v_mfma_f32_16x16x32_bf16 v[106:109], v[152:155], v[184:187], v[106:109]
	v_mfma_f32_16x16x32_bf16 v[92:95], v[140:143], v[192:195], v[92:95]
	v_mfma_f32_16x16x32_bf16 v[88:91], v[152:155], v[192:195], v[88:91]
	v_mfma_f32_16x16x32_bf16 v[76:79], v[140:143], v[200:203], v[76:79]
	v_mfma_f32_16x16x32_bf16 v[72:75], v[152:155], v[200:203], v[72:75]
	v_mfma_f32_16x16x32_bf16 v[126:129], v[148:151], v[180:183], v[126:129]
	v_mfma_f32_16x16x32_bf16 v[122:125], v[156:159], v[180:183], v[122:125]
	v_mfma_f32_16x16x32_bf16 v[110:113], v[148:151], v[188:191], v[110:113]
	v_mfma_f32_16x16x32_bf16 v[106:109], v[156:159], v[188:191], v[106:109]
	v_mfma_f32_16x16x32_bf16 v[92:95], v[148:151], v[196:199], v[92:95]
	v_mfma_f32_16x16x32_bf16 v[88:91], v[156:159], v[196:199], v[88:91]
	v_mfma_f32_16x16x32_bf16 v[76:79], v[148:151], v[204:207], v[76:79]
	v_mfma_f32_16x16x32_bf16 v[72:75], v[156:159], v[204:207], v[72:75]
	v_mfma_f32_16x16x32_bf16 v[118:121], v[160:163], v[176:179], v[118:121]
	v_mfma_f32_16x16x32_bf16 v[114:117], v[168:171], v[176:179], v[114:117]
	v_mfma_f32_16x16x32_bf16 v[102:105], v[160:163], v[184:187], v[102:105]
	v_mfma_f32_16x16x32_bf16 v[98:101], v[168:171], v[184:187], v[98:101]
	v_mfma_f32_16x16x32_bf16 v[84:87], v[160:163], v[192:195], v[84:87]
	v_mfma_f32_16x16x32_bf16 v[80:83], v[168:171], v[192:195], v[80:83]
	v_mfma_f32_16x16x32_bf16 v[68:71], v[160:163], v[200:203], v[68:71]
	v_mfma_f32_16x16x32_bf16 v[64:67], v[168:171], v[200:203], v[64:67]
	v_mfma_f32_16x16x32_bf16 v[118:121], v[164:167], v[180:183], v[118:121]
	v_mfma_f32_16x16x32_bf16 v[114:117], v[172:175], v[180:183], v[114:117]
	v_mfma_f32_16x16x32_bf16 v[102:105], v[164:167], v[188:191], v[102:105]
	v_mfma_f32_16x16x32_bf16 v[98:101], v[172:175], v[188:191], v[98:101]
	v_mfma_f32_16x16x32_bf16 v[84:87], v[164:167], v[196:199], v[84:87]
	v_mfma_f32_16x16x32_bf16 v[80:83], v[172:175], v[196:199], v[80:83]
	v_mfma_f32_16x16x32_bf16 v[68:71], v[164:167], v[204:207], v[68:71]
	v_mfma_f32_16x16x32_bf16 v[64:67], v[172:175], v[204:207], v[64:67]
	s_barrier
	s_add_i32 s30, s87, s63
	v_lshl_add_u64 v[208:209], v[208:209], 0, s[48:49]
	s_mov_b32 m0, s30
	ds_read_b128 v[176:179], v147 offset:49152
	ds_read_b128 v[180:183], v147 offset:50176
	ds_read_b128 v[184:187], v147 offset:51200
	ds_read_b128 v[188:191], v147 offset:52224
	ds_read_b128 v[192:195], v147 offset:53248
	ds_read_b128 v[196:199], v147 offset:54272
	ds_read_b128 v[200:203], v147 offset:55296
	ds_read_b128 v[204:207], v147 offset:56320
	global_load_lds_dwordx4 v[208:209], off
	s_add_i32 m0, s30, 0x2000
	s_add_u32 s30, s66, 0x40080
	v_lshl_add_u64 v[208:209], v[210:211], 0, s[48:49]
	s_addc_u32 s31, s67, 0
	s_add_i32 s66, s88, s63
	global_load_lds_dwordx4 v[208:209], off
	v_lshl_add_u64 v[208:209], s[30:31], 0, v[96:97]
	s_mov_b32 m0, s66
	s_nop 0
	global_load_lds_dwordx4 v[208:209], off
	v_lshl_add_u64 v[208:209], s[30:31], 0, v[130:131]
	s_add_i32 m0, s66, 0x2000
	s_nop 0
	global_load_lds_dwordx4 v[208:209], off
	v_lshl_add_u64 v[208:209], v[216:217], 0, s[48:49]
	s_mov_b32 m0, s80
	s_nop 0
	global_load_lds_dwordx4 v[208:209], off
	v_lshl_add_u64 v[208:209], v[218:219], 0, s[48:49]
	s_mov_b32 m0, s81
	s_nop 0
	global_load_lds_dwordx4 v[208:209], off
	s_waitcnt vmcnt(8)
	s_waitcnt lgkmcnt(0)
	s_barrier
	s_waitcnt lgkmcnt(0)
	v_mfma_f32_16x16x32_bf16 v[60:63], v[140:143], v[176:179], v[60:63]
	v_mfma_f32_16x16x32_bf16 v[56:59], v[152:155], v[176:179], v[56:59]
	v_mfma_f32_16x16x32_bf16 v[44:47], v[140:143], v[184:187], v[44:47]
	v_mfma_f32_16x16x32_bf16 v[40:43], v[152:155], v[184:187], v[40:43]
	v_mfma_f32_16x16x32_bf16 v[28:31], v[140:143], v[192:195], v[28:31]
	v_mfma_f32_16x16x32_bf16 v[24:27], v[152:155], v[192:195], v[24:27]
	v_mfma_f32_16x16x32_bf16 v[12:15], v[140:143], v[200:203], v[12:15]
	v_mfma_f32_16x16x32_bf16 v[8:11], v[152:155], v[200:203], v[8:11]
	v_mfma_f32_16x16x32_bf16 v[60:63], v[148:151], v[180:183], v[60:63]
	v_mfma_f32_16x16x32_bf16 v[56:59], v[156:159], v[180:183], v[56:59]
	v_mfma_f32_16x16x32_bf16 v[44:47], v[148:151], v[188:191], v[44:47]
	v_mfma_f32_16x16x32_bf16 v[40:43], v[156:159], v[188:191], v[40:43]
	v_mfma_f32_16x16x32_bf16 v[28:31], v[148:151], v[196:199], v[28:31]
	v_mfma_f32_16x16x32_bf16 v[24:27], v[156:159], v[196:199], v[24:27]
	v_mfma_f32_16x16x32_bf16 v[12:15], v[148:151], v[204:207], v[12:15]
	v_mfma_f32_16x16x32_bf16 v[8:11], v[156:159], v[204:207], v[8:11]
	v_mfma_f32_16x16x32_bf16 v[52:55], v[160:163], v[176:179], v[52:55]
	v_mfma_f32_16x16x32_bf16 v[48:51], v[168:171], v[176:179], v[48:51]
	v_mfma_f32_16x16x32_bf16 v[36:39], v[160:163], v[184:187], v[36:39]
	v_mfma_f32_16x16x32_bf16 v[32:35], v[168:171], v[184:187], v[32:35]
	v_mfma_f32_16x16x32_bf16 v[20:23], v[160:163], v[192:195], v[20:23]
	v_mfma_f32_16x16x32_bf16 v[16:19], v[168:171], v[192:195], v[16:19]
	v_mfma_f32_16x16x32_bf16 v[4:7], v[160:163], v[200:203], v[4:7]
	v_mfma_f32_16x16x32_bf16 v[0:3], v[168:171], v[200:203], v[0:3]
	v_mfma_f32_16x16x32_bf16 v[52:55], v[164:167], v[180:183], v[52:55]
	v_mfma_f32_16x16x32_bf16 v[48:51], v[172:175], v[180:183], v[48:51]
	v_mfma_f32_16x16x32_bf16 v[36:39], v[164:167], v[188:191], v[36:39]
	v_mfma_f32_16x16x32_bf16 v[32:35], v[172:175], v[188:191], v[32:35]
	v_mfma_f32_16x16x32_bf16 v[20:23], v[164:167], v[196:199], v[20:23]
	v_mfma_f32_16x16x32_bf16 v[16:19], v[172:175], v[196:199], v[16:19]
	v_mfma_f32_16x16x32_bf16 v[4:7], v[164:167], v[204:207], v[4:7]
	v_mfma_f32_16x16x32_bf16 v[0:3], v[172:175], v[204:207], v[0:3]
	s_barrier
	s_add_i32 s86, s86, 2
	s_add_u32 s26, s26, 0x100
	s_addc_u32 s27, s27, 0
	s_add_u32 s84, s84, 0x100
	s_addc_u32 s85, s85, 0
	s_cmp_gt_u32 s86, 13
	s_cbranch_scc0 .LBB0_733
	s_setprio 0
	s_and_b64 vcc, exec, s[14:15]
	s_cbranch_vccz .LBB0_736
	s_barrier

.LBB0_940:
	s_add_u32 s82, s22, 0x100
	s_addc_u32 s83, s23, 0
	s_add_u32 s22, s16, 0xb0080
	s_addc_u32 s23, s17, 0
	v_lshl_add_u64 v[140:141], s[22:23], 0, v[136:137]
	v_lshl_add_u64 v[142:143], s[22:23], 0, v[138:139]
	s_mov_b32 s84, -2
	s_mov_b64 s[22:23], 0
	s_cmp_eq_u32 s62, 0
	s_cbranch_scc0 .Lsprio_skip3
	s_setprio 1
.Lsprio_skip3:
.LBB0_941:
	s_add_u32 s24, s16, s22
	s_addc_u32 s25, s17, s23
	s_add_u32 s24, s24, 0x100
	s_addc_u32 s25, s25, 0
	s_add_u32 s30, s82, s22
	s_addc_u32 s31, s83, s23
	s_add_i32 s85, 0, 0x10000
	s_cmpk_eq_i32 s22, 0x1500
	s_cselect_b32 s27, s19, s25
	s_cselect_b32 s26, s18, s24
	v_add_u32_e32 v151, s85, v144
	s_cselect_b32 s25, s7, s31
	s_cselect_b32 s24, s6, s30
	s_add_i32 s86, 0, 0x14000
	ds_read_b128 v[146:149], v151
	ds_read_b128 v[152:155], v151 offset:1024
	ds_read_b128 v[156:159], v151 offset:2048
	ds_read_b128 v[160:163], v151 offset:3072
	v_add_u32_e32 v151, s86, v144
	ds_read_b128 v[164:167], v151
	ds_read_b128 v[168:171], v151 offset:1024
	ds_read_b128 v[172:175], v151 offset:2048
	ds_read_b128 v[176:179], v151 offset:3072
	v_lshl_add_u64 v[216:217], v[140:141], 0, s[22:23]
	s_add_i32 m0, s72, 0xc000
	ds_read_b128 v[180:183], v145
	ds_read_b128 v[184:187], v145 offset:1024
	ds_read_b128 v[188:191], v145 offset:2048
	ds_read_b128 v[192:195], v145 offset:3072
	ds_read_b128 v[196:199], v145 offset:4096
	ds_read_b128 v[200:203], v145 offset:5120
	ds_read_b128 v[204:207], v145 offset:6144
	ds_read_b128 v[208:211], v145 offset:7168
	global_load_lds_dwordx4 v[216:217], off
	v_lshl_add_u64 v[216:217], v[142:143], 0, s[22:23]
	s_add_i32 m0, s72, 0xe000
	s_nop 0
	global_load_lds_dwordx4 v[216:217], off
	s_waitcnt vmcnt(8)
	s_waitcnt lgkmcnt(0)
	s_barrier
	s_waitcnt lgkmcnt(0)
	v_mfma_f32_16x16x32_bf16 v[126:129], v[146:149], v[180:183], v[126:129]
	v_mfma_f32_16x16x32_bf16 v[122:125], v[156:159], v[180:183], v[122:125]
	v_mfma_f32_16x16x32_bf16 v[118:121], v[146:149], v[188:191], v[118:121]
	v_mfma_f32_16x16x32_bf16 v[110:113], v[156:159], v[188:191], v[110:113]
	v_mfma_f32_16x16x32_bf16 v[102:105], v[146:149], v[196:199], v[102:105]
	v_mfma_f32_16x16x32_bf16 v[92:95], v[156:159], v[196:199], v[92:95]
	v_mfma_f32_16x16x32_bf16 v[84:87], v[146:149], v[204:207], v[84:87]
	v_mfma_f32_16x16x32_bf16 v[76:79], v[156:159], v[204:207], v[76:79]
	v_mfma_f32_16x16x32_bf16 v[126:129], v[152:155], v[184:187], v[126:129]
	v_mfma_f32_16x16x32_bf16 v[122:125], v[160:163], v[184:187], v[122:125]
	v_mfma_f32_16x16x32_bf16 v[118:121], v[152:155], v[192:195], v[118:121]
	v_mfma_f32_16x16x32_bf16 v[110:113], v[160:163], v[192:195], v[110:113]
	v_mfma_f32_16x16x32_bf16 v[102:105], v[152:155], v[200:203], v[102:105]
	v_mfma_f32_16x16x32_bf16 v[92:95], v[160:163], v[200:203], v[92:95]
	v_mfma_f32_16x16x32_bf16 v[84:87], v[152:155], v[208:211], v[84:87]
	v_mfma_f32_16x16x32_bf16 v[76:79], v[160:163], v[208:211], v[76:79]
	v_mfma_f32_16x16x32_bf16 v[114:117], v[164:167], v[180:183], v[114:117]
	v_mfma_f32_16x16x32_bf16 v[106:109], v[172:175], v[180:183], v[106:109]
	v_mfma_f32_16x16x32_bf16 v[98:101], v[164:167], v[188:191], v[98:101]
	v_mfma_f32_16x16x32_bf16 v[88:91], v[172:175], v[188:191], v[88:91]
	v_mfma_f32_16x16x32_bf16 v[80:83], v[164:167], v[196:199], v[80:83]
	v_mfma_f32_16x16x32_bf16 v[72:75], v[172:175], v[196:199], v[72:75]
	v_mfma_f32_16x16x32_bf16 v[68:71], v[164:167], v[204:207], v[68:71]
	v_mfma_f32_16x16x32_bf16 v[64:67], v[172:175], v[204:207], v[64:67]
	v_mfma_f32_16x16x32_bf16 v[114:117], v[168:171], v[184:187], v[114:117]
	v_mfma_f32_16x16x32_bf16 v[106:109], v[176:179], v[184:187], v[106:109]
	v_mfma_f32_16x16x32_bf16 v[98:101], v[168:171], v[192:195], v[98:101]
	v_mfma_f32_16x16x32_bf16 v[88:91], v[176:179], v[192:195], v[88:91]
	v_mfma_f32_16x16x32_bf16 v[80:83], v[168:171], v[200:203], v[80:83]
	v_mfma_f32_16x16x32_bf16 v[72:75], v[176:179], v[200:203], v[72:75]
	v_mfma_f32_16x16x32_bf16 v[68:71], v[168:171], v[208:211], v[68:71]
	v_mfma_f32_16x16x32_bf16 v[64:67], v[176:179], v[208:211], v[64:67]
	s_barrier
	s_add_i32 s30, s85, s67
	v_lshl_add_u64 v[216:217], s[24:25], 0, v[96:97]
	s_mov_b32 m0, s30
	ds_read_b128 v[180:183], v145 offset:16384
	ds_read_b128 v[184:187], v145 offset:17408
	ds_read_b128 v[188:191], v145 offset:18432
	ds_read_b128 v[192:195], v145 offset:19456
	ds_read_b128 v[196:199], v145 offset:20480
	ds_read_b128 v[200:203], v145 offset:21504
	ds_read_b128 v[204:207], v145 offset:22528
	ds_read_b128 v[208:211], v145 offset:23552
	global_load_lds_dwordx4 v[216:217], off
	s_add_i32 m0, s30, 0x2000
	s_add_u32 s30, s24, 0xb0000
	v_lshl_add_u64 v[218:219], s[24:25], 0, v[134:135]
	s_addc_u32 s31, s25, 0
	s_add_i32 s85, s86, s67
	global_load_lds_dwordx4 v[218:219], off
	v_lshl_add_u64 v[220:221], s[30:31], 0, v[96:97]
	s_mov_b32 m0, s85
	v_lshl_add_u64 v[222:223], s[26:27], 0, v[132:133]
	global_load_lds_dwordx4 v[220:221], off
	v_lshl_add_u64 v[220:221], s[30:31], 0, v[134:135]
	s_add_i32 m0, s85, 0x2000
	s_nop 0
	global_load_lds_dwordx4 v[220:221], off
	v_lshl_add_u64 v[220:221], s[26:27], 0, v[130:131]
	s_mov_b32 m0, s72
	s_nop 0
	global_load_lds_dwordx4 v[220:221], off
	s_mov_b32 m0, s73
	s_nop 0
	global_load_lds_dwordx4 v[222:223], off
	s_waitcnt vmcnt(8)
	s_waitcnt lgkmcnt(0)
	s_barrier
	s_waitcnt lgkmcnt(0)
	v_mfma_f32_16x16x32_bf16 v[60:63], v[146:149], v[180:183], v[60:63]
	v_mfma_f32_16x16x32_bf16 v[56:59], v[156:159], v[180:183], v[56:59]
	v_mfma_f32_16x16x32_bf16 v[52:55], v[146:149], v[188:191], v[52:55]
	v_mfma_f32_16x16x32_bf16 v[44:47], v[156:159], v[188:191], v[44:47]
	v_mfma_f32_16x16x32_bf16 v[36:39], v[146:149], v[196:199], v[36:39]
	v_mfma_f32_16x16x32_bf16 v[28:31], v[156:159], v[196:199], v[28:31]
	v_mfma_f32_16x16x32_bf16 v[20:23], v[146:149], v[204:207], v[20:23]
	v_mfma_f32_16x16x32_bf16 v[12:15], v[156:159], v[204:207], v[12:15]
	v_mfma_f32_16x16x32_bf16 v[60:63], v[152:155], v[184:187], v[60:63]
	v_mfma_f32_16x16x32_bf16 v[56:59], v[160:163], v[184:187], v[56:59]
	v_mfma_f32_16x16x32_bf16 v[52:55], v[152:155], v[192:195], v[52:55]
	v_mfma_f32_16x16x32_bf16 v[44:47], v[160:163], v[192:195], v[44:47]
	v_mfma_f32_16x16x32_bf16 v[36:39], v[152:155], v[200:203], v[36:39]
	v_mfma_f32_16x16x32_bf16 v[28:31], v[160:163], v[200:203], v[28:31]
	v_mfma_f32_16x16x32_bf16 v[20:23], v[152:155], v[208:211], v[20:23]
	v_mfma_f32_16x16x32_bf16 v[12:15], v[160:163], v[208:211], v[12:15]
	v_mfma_f32_16x16x32_bf16 v[48:51], v[164:167], v[180:183], v[48:51]
	v_mfma_f32_16x16x32_bf16 v[40:43], v[172:175], v[180:183], v[40:43]
	v_mfma_f32_16x16x32_bf16 v[32:35], v[164:167], v[188:191], v[32:35]
	v_mfma_f32_16x16x32_bf16 v[24:27], v[172:175], v[188:191], v[24:27]
	v_mfma_f32_16x16x32_bf16 v[16:19], v[164:167], v[196:199], v[16:19]
	v_mfma_f32_16x16x32_bf16 v[8:11], v[172:175], v[196:199], v[8:11]
	v_mfma_f32_16x16x32_bf16 v[4:7], v[164:167], v[204:207], v[4:7]
	v_mfma_f32_16x16x32_bf16 v[0:3], v[172:175], v[204:207], v[0:3]
	v_mfma_f32_16x16x32_bf16 v[48:51], v[168:171], v[184:187], v[48:51]
	v_mfma_f32_16x16x32_bf16 v[40:43], v[176:179], v[184:187], v[40:43]
	v_mfma_f32_16x16x32_bf16 v[32:35], v[168:171], v[192:195], v[32:35]
	v_mfma_f32_16x16x32_bf16 v[24:27], v[176:179], v[192:195], v[24:27]
	v_mfma_f32_16x16x32_bf16 v[16:19], v[168:171], v[200:203], v[16:19]
	v_mfma_f32_16x16x32_bf16 v[8:11], v[176:179], v[200:203], v[8:11]
	v_mfma_f32_16x16x32_bf16 v[4:7], v[168:171], v[208:211], v[4:7]
	v_mfma_f32_16x16x32_bf16 v[0:3], v[176:179], v[208:211], v[0:3]
	s_barrier
	s_add_i32 s30, 0, 0x18000
	v_add_u32_e32 v151, s30, v144
	s_add_i32 s31, 0, 0x1c000
	ds_read_b128 v[146:149], v151
	ds_read_b128 v[152:155], v151 offset:1024
	ds_read_b128 v[156:159], v151 offset:2048
	ds_read_b128 v[160:163], v151 offset:3072
	v_add_u32_e32 v151, s31, v144
	ds_read_b128 v[164:167], v151
	ds_read_b128 v[168:171], v151 offset:1024
	ds_read_b128 v[172:175], v151 offset:2048
	ds_read_b128 v[176:179], v151 offset:3072
	s_add_u32 s26, s26, 0xb0000
	s_addc_u32 s27, s27, 0
	s_mov_b32 m0, s74
	v_lshl_add_u64 v[224:225], s[26:27], 0, v[130:131]
	ds_read_b128 v[180:183], v145 offset:32768
	ds_read_b128 v[184:187], v145 offset:33792
	ds_read_b128 v[188:191], v145 offset:34816
	ds_read_b128 v[192:195], v145 offset:35840
	ds_read_b128 v[196:199], v145 offset:36864
	ds_read_b128 v[200:203], v145 offset:37888
	ds_read_b128 v[204:207], v145 offset:38912
	ds_read_b128 v[208:211], v145 offset:39936
	global_load_lds_dwordx4 v[224:225], off
	v_lshl_add_u64 v[224:225], s[26:27], 0, v[132:133]
	s_mov_b32 m0, s75
	s_nop 0
	global_load_lds_dwordx4 v[224:225], off
	s_waitcnt vmcnt(8)
	s_waitcnt lgkmcnt(0)
	s_barrier
	s_waitcnt lgkmcnt(0)
	v_mfma_f32_16x16x32_bf16 v[126:129], v[146:149], v[180:183], v[126:129]
	v_mfma_f32_16x16x32_bf16 v[122:125], v[156:159], v[180:183], v[122:125]
	v_mfma_f32_16x16x32_bf16 v[118:121], v[146:149], v[188:191], v[118:121]
	v_mfma_f32_16x16x32_bf16 v[110:113], v[156:159], v[188:191], v[110:113]
	v_mfma_f32_16x16x32_bf16 v[102:105], v[146:149], v[196:199], v[102:105]
	v_mfma_f32_16x16x32_bf16 v[92:95], v[156:159], v[196:199], v[92:95]
	v_mfma_f32_16x16x32_bf16 v[84:87], v[146:149], v[204:207], v[84:87]
	v_mfma_f32_16x16x32_bf16 v[76:79], v[156:159], v[204:207], v[76:79]
	v_mfma_f32_16x16x32_bf16 v[126:129], v[152:155], v[184:187], v[126:129]
	v_mfma_f32_16x16x32_bf16 v[122:125], v[160:163], v[184:187], v[122:125]
	v_mfma_f32_16x16x32_bf16 v[118:121], v[152:155], v[192:195], v[118:121]
	v_mfma_f32_16x16x32_bf16 v[110:113], v[160:163], v[192:195], v[110:113]
	v_mfma_f32_16x16x32_bf16 v[102:105], v[152:155], v[200:203], v[102:105]
	v_mfma_f32_16x16x32_bf16 v[92:95], v[160:163], v[200:203], v[92:95]
	v_mfma_f32_16x16x32_bf16 v[84:87], v[152:155], v[208:211], v[84:87]
	v_mfma_f32_16x16x32_bf16 v[76:79], v[160:163], v[208:211], v[76:79]
	v_mfma_f32_16x16x32_bf16 v[114:117], v[164:167], v[180:183], v[114:117]
	v_mfma_f32_16x16x32_bf16 v[106:109], v[172:175], v[180:183], v[106:109]
	v_mfma_f32_16x16x32_bf16 v[98:101], v[164:167], v[188:191], v[98:101]
	v_mfma_f32_16x16x32_bf16 v[88:91], v[172:175], v[188:191], v[88:91]
	v_mfma_f32_16x16x32_bf16 v[80:83], v[164:167], v[196:199], v[80:83]
	v_mfma_f32_16x16x32_bf16 v[72:75], v[172:175], v[196:199], v[72:75]
	v_mfma_f32_16x16x32_bf16 v[68:71], v[164:167], v[204:207], v[68:71]
	v_mfma_f32_16x16x32_bf16 v[64:67], v[172:175], v[204:207], v[64:67]
	v_mfma_f32_16x16x32_bf16 v[114:117], v[168:171], v[184:187], v[114:117]
	v_mfma_f32_16x16x32_bf16 v[106:109], v[176:179], v[184:187], v[106:109]
	v_mfma_f32_16x16x32_bf16 v[98:101], v[168:171], v[192:195], v[98:101]
	v_mfma_f32_16x16x32_bf16 v[88:91], v[176:179], v[192:195], v[88:91]
	v_mfma_f32_16x16x32_bf16 v[80:83], v[168:171], v[200:203], v[80:83]
	v_mfma_f32_16x16x32_bf16 v[72:75], v[176:179], v[200:203], v[72:75]
	v_mfma_f32_16x16x32_bf16 v[68:71], v[168:171], v[208:211], v[68:71]
	v_mfma_f32_16x16x32_bf16 v[64:67], v[176:179], v[208:211], v[64:67]
	s_barrier
	s_add_i32 s26, s30, s67
	v_lshl_add_u64 v[216:217], v[216:217], 0, s[48:49]
	s_mov_b32 m0, s26
	ds_read_b128 v[180:183], v145 offset:49152
	ds_read_b128 v[184:187], v145 offset:50176
	ds_read_b128 v[188:191], v145 offset:51200
	ds_read_b128 v[192:195], v145 offset:52224
	ds_read_b128 v[196:199], v145 offset:53248
	ds_read_b128 v[200:203], v145 offset:54272
	ds_read_b128 v[204:207], v145 offset:55296
	ds_read_b128 v[208:211], v145 offset:56320
	global_load_lds_dwordx4 v[216:217], off
	s_add_i32 m0, s26, 0x2000
	s_add_u32 s24, s24, 0xb0080
	v_lshl_add_u64 v[216:217], v[218:219], 0, s[48:49]
	s_addc_u32 s25, s25, 0
	s_add_i32 s26, s31, s67
	global_load_lds_dwordx4 v[216:217], off
	v_lshl_add_u64 v[216:217], s[24:25], 0, v[96:97]
	s_mov_b32 m0, s26
	s_nop 0
	global_load_lds_dwordx4 v[216:217], off
	v_lshl_add_u64 v[216:217], s[24:25], 0, v[134:135]
	s_add_i32 m0, s26, 0x2000
	s_nop 0
	global_load_lds_dwordx4 v[216:217], off
	v_lshl_add_u64 v[216:217], v[220:221], 0, s[48:49]
	s_mov_b32 m0, s76
	s_nop 0
	global_load_lds_dwordx4 v[216:217], off
	v_lshl_add_u64 v[216:217], v[222:223], 0, s[48:49]
	s_mov_b32 m0, s77
	s_nop 0
	global_load_lds_dwordx4 v[216:217], off
	s_waitcnt vmcnt(8)
	s_waitcnt lgkmcnt(0)
	s_barrier
	s_waitcnt lgkmcnt(0)
	v_mfma_f32_16x16x32_bf16 v[60:63], v[146:149], v[180:183], v[60:63]
	v_mfma_f32_16x16x32_bf16 v[56:59], v[156:159], v[180:183], v[56:59]
	v_mfma_f32_16x16x32_bf16 v[52:55], v[146:149], v[188:191], v[52:55]
	v_mfma_f32_16x16x32_bf16 v[44:47], v[156:159], v[188:191], v[44:47]
	v_mfma_f32_16x16x32_bf16 v[36:39], v[146:149], v[196:199], v[36:39]
	v_mfma_f32_16x16x32_bf16 v[28:31], v[156:159], v[196:199], v[28:31]
	v_mfma_f32_16x16x32_bf16 v[20:23], v[146:149], v[204:207], v[20:23]
	v_mfma_f32_16x16x32_bf16 v[12:15], v[156:159], v[204:207], v[12:15]
	v_mfma_f32_16x16x32_bf16 v[60:63], v[152:155], v[184:187], v[60:63]
	v_mfma_f32_16x16x32_bf16 v[56:59], v[160:163], v[184:187], v[56:59]
	v_mfma_f32_16x16x32_bf16 v[52:55], v[152:155], v[192:195], v[52:55]
	v_mfma_f32_16x16x32_bf16 v[44:47], v[160:163], v[192:195], v[44:47]
	v_mfma_f32_16x16x32_bf16 v[36:39], v[152:155], v[200:203], v[36:39]
	v_mfma_f32_16x16x32_bf16 v[28:31], v[160:163], v[200:203], v[28:31]
	v_mfma_f32_16x16x32_bf16 v[20:23], v[152:155], v[208:211], v[20:23]
	v_mfma_f32_16x16x32_bf16 v[12:15], v[160:163], v[208:211], v[12:15]
	v_mfma_f32_16x16x32_bf16 v[48:51], v[164:167], v[180:183], v[48:51]
	v_mfma_f32_16x16x32_bf16 v[40:43], v[172:175], v[180:183], v[40:43]
	v_mfma_f32_16x16x32_bf16 v[32:35], v[164:167], v[188:191], v[32:35]
	v_mfma_f32_16x16x32_bf16 v[24:27], v[172:175], v[188:191], v[24:27]
	v_mfma_f32_16x16x32_bf16 v[16:19], v[164:167], v[196:199], v[16:19]
	v_mfma_f32_16x16x32_bf16 v[8:11], v[172:175], v[196:199], v[8:11]
	v_mfma_f32_16x16x32_bf16 v[4:7], v[164:167], v[204:207], v[4:7]
	v_mfma_f32_16x16x32_bf16 v[0:3], v[172:175], v[204:207], v[0:3]
	v_mfma_f32_16x16x32_bf16 v[48:51], v[168:171], v[184:187], v[48:51]
	v_mfma_f32_16x16x32_bf16 v[40:43], v[176:179], v[184:187], v[40:43]
	v_mfma_f32_16x16x32_bf16 v[32:35], v[168:171], v[192:195], v[32:35]
	v_mfma_f32_16x16x32_bf16 v[24:27], v[176:179], v[192:195], v[24:27]
	v_mfma_f32_16x16x32_bf16 v[16:19], v[168:171], v[200:203], v[16:19]
	v_mfma_f32_16x16x32_bf16 v[8:11], v[176:179], v[200:203], v[8:11]
	v_mfma_f32_16x16x32_bf16 v[4:7], v[168:171], v[208:211], v[4:7]
	v_mfma_f32_16x16x32_bf16 v[0:3], v[176:179], v[208:211], v[0:3]
	s_barrier
	s_add_i32 s84, s84, 2
	s_add_u32 s22, s22, 0x100
	s_addc_u32 s23, s23, 0
	s_cmp_gt_u32 s84, 41
	s_cbranch_scc0 .LBB0_941
	s_setprio 0
	s_add_u32 s22, s82, 0xffffff00
	s_addc_u32 s23, s83, -1
	s_and_b64 vcc, exec, s[4:5]
	s_cbranch_vccnz .LBB0_944
	v_mov_b32_e32 v0, 0
	s_mov_b32 s20, s79
	s_mov_b32 s63, s80
	s_mov_b64 s[16:17], s[18:19]
	s_mov_b32 s78, s81
	v_mov_b32_e32 v1, v0
	v_mov_b32_e32 v2, v0
	v_mov_b32_e32 v3, v0
	v_mov_b32_e32 v4, v0
	v_mov_b32_e32 v5, v0
	v_mov_b32_e32 v6, v0
	v_mov_b32_e32 v7, v0
	v_mov_b32_e32 v8, v0
	v_mov_b32_e32 v9, v0
	v_mov_b32_e32 v10, v0
	v_mov_b32_e32 v11, v0
	v_mov_b32_e32 v16, v0
	v_mov_b32_e32 v17, v0
	v_mov_b32_e32 v18, v0
	v_mov_b32_e32 v19, v0
	v_mov_b32_e32 v24, v0
	v_mov_b32_e32 v25, v0
	v_mov_b32_e32 v26, v0
	v_mov_b32_e32 v27, v0
	v_mov_b32_e32 v32, v0
	v_mov_b32_e32 v33, v0
	v_mov_b32_e32 v34, v0
	v_mov_b32_e32 v35, v0
	v_mov_b32_e32 v40, v0
	v_mov_b32_e32 v41, v0
	v_mov_b32_e32 v42, v0
	v_mov_b32_e32 v43, v0
	v_mov_b32_e32 v48, v0
	v_mov_b32_e32 v49, v0
	v_mov_b32_e32 v50, v0
	v_mov_b32_e32 v51, v0
	v_mov_b32_e32 v12, v0
	v_mov_b32_e32 v13, v0
	v_mov_b32_e32 v14, v0
	v_mov_b32_e32 v15, v0
	v_mov_b32_e32 v20, v0
	v_mov_b32_e32 v21, v0
	v_mov_b32_e32 v22, v0
	v_mov_b32_e32 v23, v0
	v_mov_b32_e32 v28, v0
	v_mov_b32_e32 v29, v0
	v_mov_b32_e32 v30, v0
	v_mov_b32_e32 v31, v0
	v_mov_b32_e32 v36, v0
	v_mov_b32_e32 v37, v0
	v_mov_b32_e32 v38, v0
	v_mov_b32_e32 v39, v0
	v_mov_b32_e32 v44, v0
	v_mov_b32_e32 v45, v0
	v_mov_b32_e32 v46, v0
	v_mov_b32_e32 v47, v0
	v_mov_b32_e32 v52, v0
	v_mov_b32_e32 v53, v0
	v_mov_b32_e32 v54, v0
	v_mov_b32_e32 v55, v0
	v_mov_b32_e32 v56, v0
	v_mov_b32_e32 v57, v0
	v_mov_b32_e32 v58, v0
	v_mov_b32_e32 v59, v0
	v_mov_b32_e32 v60, v0
	v_mov_b32_e32 v61, v0
	v_mov_b32_e32 v62, v0
	v_mov_b32_e32 v63, v0
	v_mov_b32_e32 v64, v0
	v_mov_b32_e32 v65, v0
	v_mov_b32_e32 v66, v0
	v_mov_b32_e32 v67, v0
	v_mov_b32_e32 v68, v0
	v_mov_b32_e32 v69, v0
	v_mov_b32_e32 v70, v0
	v_mov_b32_e32 v71, v0
	v_mov_b32_e32 v72, v0
	v_mov_b32_e32 v73, v0
	v_mov_b32_e32 v74, v0
	v_mov_b32_e32 v75, v0
	v_mov_b32_e32 v80, v0
	v_mov_b32_e32 v81, v0
	v_mov_b32_e32 v82, v0
	v_mov_b32_e32 v83, v0
	v_mov_b32_e32 v88, v0
	v_mov_b32_e32 v89, v0
	v_mov_b32_e32 v90, v0
	v_mov_b32_e32 v91, v0
	v_mov_b32_e32 v98, v0
	v_mov_b32_e32 v99, v0
	v_mov_b32_e32 v100, v0
	v_mov_b32_e32 v101, v0
	v_mov_b32_e32 v106, v0
	v_mov_b32_e32 v107, v0
	v_mov_b32_e32 v108, v0
	v_mov_b32_e32 v109, v0
	v_mov_b32_e32 v114, v0
	v_mov_b32_e32 v115, v0
	v_mov_b32_e32 v116, v0
	v_mov_b32_e32 v117, v0
	v_mov_b32_e32 v76, v0
	v_mov_b32_e32 v77, v0
	v_mov_b32_e32 v78, v0
	v_mov_b32_e32 v79, v0
	v_mov_b32_e32 v84, v0
	v_mov_b32_e32 v85, v0
	v_mov_b32_e32 v86, v0
	v_mov_b32_e32 v87, v0
	v_mov_b32_e32 v92, v0
	v_mov_b32_e32 v93, v0
	v_mov_b32_e32 v94, v0
	v_mov_b32_e32 v95, v0
	v_mov_b32_e32 v102, v0
	v_mov_b32_e32 v103, v0
	v_mov_b32_e32 v104, v0
	v_mov_b32_e32 v105, v0
	v_mov_b32_e32 v110, v0
	v_mov_b32_e32 v111, v0
	v_mov_b32_e32 v112, v0
	v_mov_b32_e32 v113, v0
	v_mov_b32_e32 v118, v0
	v_mov_b32_e32 v119, v0
	v_mov_b32_e32 v120, v0
	v_mov_b32_e32 v121, v0
	v_mov_b32_e32 v122, v0
	v_mov_b32_e32 v123, v0
	v_mov_b32_e32 v124, v0
	v_mov_b32_e32 v125, v0
	v_mov_b32_e32 v126, v0
	v_mov_b32_e32 v127, v0
	v_mov_b32_e32 v128, v0
	v_mov_b32_e32 v129, v0
	s_andn2_b64 vcc, exec, s[2:3]
	s_cbranch_vccnz .LBB0_945
	s_branch .LBB0_946
